# v045 + the s_nop after each m0 write replaced by moving the DMA address v_lshl_add_u64 between m0 write and global_load_lds (50 sites)
# baseline (speedup 1.0000x reference)
; #define PG8_STAGE(bufoff, gbase, voff) do { _Pragma("unroll") for (int _i = 0; _i < 2; ++_i) \
;         __builtin_amdgcn_global_load_lds((const unsigned*)((const char*)(gbase) + (voff)[_i]), (LAS unsigned*)(lds + (bufoff) + ldsw + _i * 8192), 16, 0, 0); } while (0)
; #define PG8_LDA(dst, b, h) do { _Pragma("unroll") for (int m = 0; m < 4; ++m) _Pragma("unroll") for (int k = 0; k < 2; ++k) dst[m][k] = *(const LAS bf16x8*)(lds + PG8_SA(b, h) + aoff + m * 2048 + k * 1024); } while (0)
; #define PG8_LDB(dst, b, h) do { _Pragma("unroll") for (int n = 0; n < 2; ++n) _Pragma("unroll") for (int k = 0; k < 2; ++k) dst[n][k] = *(const LAS bf16x8*)(lds + PG8_SB(b, h) + boff + n * 2048 + k * 1024); } while (0)
; #define PG8_MMA(ai, bj, At, Bt) do { __builtin_amdgcn_s_setprio(1); _Pragma("unroll") for (int m = 0; m < 4; ++m) _Pragma("unroll") for (int n = 0; n < 2; ++n) _Pragma("unroll") for (int k = 0; k < 2; ++k) \
;         acc[ai][bj][m][n] = __builtin_amdgcn_mfma_f32_16x16x32_bf16(Bt[n][k], At[m][k], acc[ai][bj][m][n], 0, 0, 0); __builtin_amdgcn_s_setprio(0); } while (0)
; #define PG8_WAIT_V(n) asm volatile("s_waitcnt vmcnt(" #n ")" ::: "memory")
; #define PG8_WAIT_L(n) asm volatile("s_waitcnt lgkmcnt(" #n ")" ::: "memory")
; template <class Epi, class Sched, bool ALIGN_EPI = false, bool SP2 = false>
; __device__ __forceinline__ void gemm_phase(LAS unsigned char* lds, const Gemm g, const Sched& S, const Epi& E) {
;     ...
;         for (int t = 0; t < nt; t += 2) {
;             const bool last = (t == nt - 2);
;             const char* a1 = cA + (size_t)(t + 1) * kstep;
;             const char* a2 = last ? nA : cA + (size_t)(t + 2) * kstep; const char* b2 = last ? nB : cB + (size_t)(t + 2) * kstep;
;             const char* a3 = a2 + kstep; const char* b3 = b2 + kstep;
;             if (last && has_next) S.a_ready(nxt);
;             if constexpr (SP2) {
;             PG8_LDB(B0, 0, 0); PG8_LDB(B1, 0, 1); PG8_SCHED; PG8_LDA(At, 0, 0); PG8_STAGE(PG8_SA(1, 1), a1 + hstepA, voffA);
;             PG8_WAIT_V(8); PG8_WAIT_L(0); PG8_BAR; PG8_MMA(0, 0, At, B0); PG8_MMA(0, 1, At, B1); PG8_BAR; PG8_SCHED;
;             PG8_LDA(At, 0, 1); PG8_STAGE(PG8_SB(0, 0), b2, voffB); PG8_STAGE(PG8_SB(0, 1), b2 + hstepB, voffB); PG8_STAGE(PG8_SA(0, 0), a2, voffA);
;             PG8_WAIT_V(8); PG8_WAIT_L(0); PG8_BAR; PG8_MMA(1, 0, At, B0); PG8_MMA(1, 1, At, B1); PG8_BAR; PG8_SCHED;
.LBB0_349:
	ds_read_b128 v[156:159], v149
	ds_read_b128 v[160:163], v149 offset:1024
	ds_read_b128 v[164:167], v149 offset:2048
	ds_read_b128 v[168:171], v149 offset:3072
	ds_read_b128 v[172:175], v150
	ds_read_b128 v[176:179], v150 offset:1024
	ds_read_b128 v[180:183], v150 offset:2048
	ds_read_b128 v[184:187], v150 offset:3072
	s_add_u32 s24, s22, 0xfff80080
	s_addc_u32 s25, s23, -1
	s_cmp_eq_u32 s58, 28
	s_cselect_b32 s27, s15, s25
	s_cselect_b32 s26, s47, s24
	s_cselect_b32 s25, s13, s55
	s_cselect_b32 s24, s50, s51
	v_lshl_add_u64 v[146:147], s[22:23], 0, v[138:139]
	s_add_i32 m0, s21, 0xc000
	ds_read_b128 v[188:191], v151
	ds_read_b128 v[192:195], v151 offset:1024
	ds_read_b128 v[196:199], v151 offset:2048
	ds_read_b128 v[200:203], v151 offset:3072
	ds_read_b128 v[204:207], v151 offset:4096
	ds_read_b128 v[208:211], v151 offset:5120
	ds_read_b128 v[212:215], v151 offset:6144
	ds_read_b128 v[216:219], v151 offset:7168
	global_load_lds_dwordx4 v[146:147], off
	s_add_i32 m0, s21, 0xe000
	v_lshl_add_u64 v[146:147], s[22:23], 0, v[140:141]
	global_load_lds_dwordx4 v[146:147], off
	s_waitcnt vmcnt(8) lgkmcnt(0)
	s_setprio 1
	s_barrier
	v_mfma_f32_16x16x32_bf16 v[126:129], v[156:159], v[188:191], v[126:129]
	v_mfma_f32_16x16x32_bf16 v[122:125], v[164:167], v[188:191], v[122:125]
	v_mfma_f32_16x16x32_bf16 v[118:121], v[156:159], v[196:199], v[118:121]
	v_mfma_f32_16x16x32_bf16 v[110:113], v[164:167], v[196:199], v[110:113]
	v_mfma_f32_16x16x32_bf16 v[102:105], v[156:159], v[204:207], v[102:105]
	v_mfma_f32_16x16x32_bf16 v[94:97], v[164:167], v[204:207], v[94:97]
	v_mfma_f32_16x16x32_bf16 v[86:89], v[156:159], v[212:215], v[86:89]
	v_mfma_f32_16x16x32_bf16 v[78:81], v[164:167], v[212:215], v[78:81]
	v_mfma_f32_16x16x32_bf16 v[126:129], v[160:163], v[192:195], v[126:129]
	v_mfma_f32_16x16x32_bf16 v[122:125], v[168:171], v[192:195], v[122:125]
	v_mfma_f32_16x16x32_bf16 v[118:121], v[160:163], v[200:203], v[118:121]
	v_mfma_f32_16x16x32_bf16 v[110:113], v[168:171], v[200:203], v[110:113]
	v_mfma_f32_16x16x32_bf16 v[102:105], v[160:163], v[208:211], v[102:105]
	v_mfma_f32_16x16x32_bf16 v[94:97], v[168:171], v[208:211], v[94:97]
	v_mfma_f32_16x16x32_bf16 v[86:89], v[160:163], v[216:219], v[86:89]
	v_mfma_f32_16x16x32_bf16 v[78:81], v[168:171], v[216:219], v[78:81]
	s_setprio 0
	s_setprio 1
	v_mfma_f32_16x16x32_bf16 v[114:117], v[172:175], v[188:191], v[114:117]
	v_mfma_f32_16x16x32_bf16 v[106:109], v[180:183], v[188:191], v[106:109]
	v_mfma_f32_16x16x32_bf16 v[98:101], v[172:175], v[196:199], v[98:101]
	v_mfma_f32_16x16x32_bf16 v[90:93], v[180:183], v[196:199], v[90:93]
	v_mfma_f32_16x16x32_bf16 v[82:85], v[172:175], v[204:207], v[82:85]
	v_mfma_f32_16x16x32_bf16 v[74:77], v[180:183], v[204:207], v[74:77]
	v_mfma_f32_16x16x32_bf16 v[70:73], v[172:175], v[212:215], v[70:73]
	v_mfma_f32_16x16x32_bf16 v[66:69], v[180:183], v[212:215], v[66:69]
	v_mfma_f32_16x16x32_bf16 v[114:117], v[176:179], v[192:195], v[114:117]
	v_mfma_f32_16x16x32_bf16 v[106:109], v[184:187], v[192:195], v[106:109]
	v_mfma_f32_16x16x32_bf16 v[98:101], v[176:179], v[200:203], v[98:101]
	v_mfma_f32_16x16x32_bf16 v[90:93], v[184:187], v[200:203], v[90:93]
	v_mfma_f32_16x16x32_bf16 v[82:85], v[176:179], v[208:211], v[82:85]
	v_mfma_f32_16x16x32_bf16 v[74:77], v[184:187], v[208:211], v[74:77]
	v_mfma_f32_16x16x32_bf16 v[70:73], v[176:179], v[216:219], v[70:73]
	v_mfma_f32_16x16x32_bf16 v[66:69], v[184:187], v[216:219], v[66:69]
	s_setprio 0
	s_barrier
	s_add_i32 s59, s40, s28
	v_lshl_add_u64 v[146:147], s[24:25], 0, v[134:135]
	s_mov_b32 m0, s59
	ds_read_b128 v[188:191], v151 offset:16384
	ds_read_b128 v[192:195], v151 offset:17408
	ds_read_b128 v[196:199], v151 offset:18432
	ds_read_b128 v[200:203], v151 offset:19456
	ds_read_b128 v[204:207], v151 offset:20480
	ds_read_b128 v[208:211], v151 offset:21504
	ds_read_b128 v[212:215], v151 offset:22528
	ds_read_b128 v[216:219], v151 offset:23552
	global_load_lds_dwordx4 v[146:147], off
	s_add_i32 m0, s59, 0x2000
	s_add_u32 s60, s24, 0x80000
	v_lshl_add_u64 v[220:221], s[24:25], 0, v[130:131]
	s_addc_u32 s61, s25, 0
	s_add_i32 s59, s41, s28
	global_load_lds_dwordx4 v[220:221], off
	v_lshl_add_u64 v[222:223], s[60:61], 0, v[134:135]
	s_mov_b32 m0, s59
	v_lshl_add_u64 v[224:225], s[26:27], 0, v[132:133]
	global_load_lds_dwordx4 v[222:223], off
	s_add_i32 m0, s59, 0x2000
	v_lshl_add_u64 v[222:223], s[60:61], 0, v[130:131]
	global_load_lds_dwordx4 v[222:223], off
	s_mov_b32 m0, s21
	v_lshl_add_u64 v[222:223], s[26:27], 0, v[136:137]
	global_load_lds_dwordx4 v[222:223], off
	s_mov_b32 m0, s31
	s_nop 0
	global_load_lds_dwordx4 v[224:225], off
	s_waitcnt vmcnt(8) lgkmcnt(0)
	s_setprio 1
	s_barrier
; #define PG8_STAGE(bufoff, gbase, voff) do { _Pragma("unroll") for (int _i = 0; _i < 2; ++_i) \
;         __builtin_amdgcn_global_load_lds((const unsigned*)((const char*)(gbase) + (voff)[_i]), (LAS unsigned*)(lds + (bufoff) + ldsw + _i * 8192), 16, 0, 0); } while (0)
; #define PG8_LDA(dst, b, h) do { _Pragma("unroll") for (int m = 0; m < 4; ++m) _Pragma("unroll") for (int k = 0; k < 2; ++k) dst[m][k] = *(const LAS bf16x8*)(lds + PG8_SA(b, h) + aoff + m * 2048 + k * 1024); } while (0)
; #define PG8_LDB(dst, b, h) do { _Pragma("unroll") for (int n = 0; n < 2; ++n) _Pragma("unroll") for (int k = 0; k < 2; ++k) dst[n][k] = *(const LAS bf16x8*)(lds + PG8_SB(b, h) + boff + n * 2048 + k * 1024); } while (0)
; #define PG8_MMA(ai, bj, At, Bt) do { __builtin_amdgcn_s_setprio(1); _Pragma("unroll") for (int m = 0; m < 4; ++m) _Pragma("unroll") for (int n = 0; n < 2; ++n) _Pragma("unroll") for (int k = 0; k < 2; ++k) \
;         acc[ai][bj][m][n] = __builtin_amdgcn_mfma_f32_16x16x32_bf16(Bt[n][k], At[m][k], acc[ai][bj][m][n], 0, 0, 0); __builtin_amdgcn_s_setprio(0); } while (0)
; #define PG8_WAIT_V(n) asm volatile("s_waitcnt vmcnt(" #n ")" ::: "memory")
; #define PG8_WAIT_L(n) asm volatile("s_waitcnt lgkmcnt(" #n ")" ::: "memory")
; #define PG8_BAR __builtin_amdgcn_s_barrier()
; #define PG8_SCHED __builtin_amdgcn_sched_barrier(0)
; template <class Epi, class Sched, bool ALIGN_EPI = false, bool SP2 = false>
; __device__ __forceinline__ void gemm_phase(LAS unsigned char* lds, const Gemm g, const Sched& S, const Epi& E) {
;     ...
;             PG8_WAIT_V(8); PG8_WAIT_L(0); PG8_BAR; PG8_MMA(1, 0, At, B0); PG8_MMA(1, 1, At, B1); PG8_BAR; PG8_SCHED;
;             PG8_LDB(B0, 1, 0); PG8_LDB(B1, 1, 1); PG8_SCHED; PG8_LDA(At, 1, 0); PG8_STAGE(PG8_SA(0, 1), a2 + hstepA, voffA);
;             PG8_WAIT_V(8); PG8_WAIT_L(0); PG8_BAR; PG8_MMA(0, 0, At, B0); PG8_MMA(0, 1, At, B1); PG8_BAR; PG8_SCHED;
	v_mfma_f32_16x16x32_bf16 v[62:65], v[156:159], v[188:191], v[62:65]
	v_mfma_f32_16x16x32_bf16 v[58:61], v[164:167], v[188:191], v[58:61]
	v_mfma_f32_16x16x32_bf16 v[54:57], v[156:159], v[196:199], v[54:57]
	v_mfma_f32_16x16x32_bf16 v[46:49], v[164:167], v[196:199], v[46:49]
	v_mfma_f32_16x16x32_bf16 v[38:41], v[156:159], v[204:207], v[38:41]
	v_mfma_f32_16x16x32_bf16 v[30:33], v[164:167], v[204:207], v[30:33]
	v_mfma_f32_16x16x32_bf16 v[22:25], v[156:159], v[212:215], v[22:25]
	v_mfma_f32_16x16x32_bf16 v[14:17], v[164:167], v[212:215], v[14:17]
	v_mfma_f32_16x16x32_bf16 v[62:65], v[160:163], v[192:195], v[62:65]
	v_mfma_f32_16x16x32_bf16 v[58:61], v[168:171], v[192:195], v[58:61]
	v_mfma_f32_16x16x32_bf16 v[54:57], v[160:163], v[200:203], v[54:57]
	v_mfma_f32_16x16x32_bf16 v[46:49], v[168:171], v[200:203], v[46:49]
	v_mfma_f32_16x16x32_bf16 v[38:41], v[160:163], v[208:211], v[38:41]
	v_mfma_f32_16x16x32_bf16 v[30:33], v[168:171], v[208:211], v[30:33]
	v_mfma_f32_16x16x32_bf16 v[22:25], v[160:163], v[216:219], v[22:25]
	v_mfma_f32_16x16x32_bf16 v[14:17], v[168:171], v[216:219], v[14:17]
	s_setprio 0
	s_setprio 1
	v_mfma_f32_16x16x32_bf16 v[50:53], v[172:175], v[188:191], v[50:53]
	v_mfma_f32_16x16x32_bf16 v[42:45], v[180:183], v[188:191], v[42:45]
	v_mfma_f32_16x16x32_bf16 v[34:37], v[172:175], v[196:199], v[34:37]
	v_mfma_f32_16x16x32_bf16 v[26:29], v[180:183], v[196:199], v[26:29]
	v_mfma_f32_16x16x32_bf16 v[18:21], v[172:175], v[204:207], v[18:21]
	v_mfma_f32_16x16x32_bf16 v[10:13], v[180:183], v[204:207], v[10:13]
	v_mfma_f32_16x16x32_bf16 v[6:9], v[172:175], v[212:215], v[6:9]
	v_mfma_f32_16x16x32_bf16 v[2:5], v[180:183], v[212:215], v[2:5]
	v_mfma_f32_16x16x32_bf16 v[50:53], v[176:179], v[192:195], v[50:53]
	v_mfma_f32_16x16x32_bf16 v[42:45], v[184:187], v[192:195], v[42:45]
	v_mfma_f32_16x16x32_bf16 v[34:37], v[176:179], v[200:203], v[34:37]
	v_mfma_f32_16x16x32_bf16 v[26:29], v[184:187], v[200:203], v[26:29]
	v_mfma_f32_16x16x32_bf16 v[18:21], v[176:179], v[208:211], v[18:21]
	v_mfma_f32_16x16x32_bf16 v[10:13], v[184:187], v[208:211], v[10:13]
	v_mfma_f32_16x16x32_bf16 v[6:9], v[176:179], v[216:219], v[6:9]
	v_mfma_f32_16x16x32_bf16 v[2:5], v[184:187], v[216:219], v[2:5]
	s_setprio 0
	s_barrier
	ds_read_b128 v[156:159], v153
	ds_read_b128 v[160:163], v153 offset:1024
	ds_read_b128 v[164:167], v153 offset:2048
	ds_read_b128 v[168:171], v153 offset:3072
	ds_read_b128 v[172:175], v154
	ds_read_b128 v[176:179], v154 offset:1024
	ds_read_b128 v[180:183], v154 offset:2048
	ds_read_b128 v[184:187], v154 offset:3072
	s_add_u32 s26, s26, 0x80000
	s_addc_u32 s27, s27, 0
	s_mov_b32 m0, s33
	v_lshl_add_u64 v[226:227], s[26:27], 0, v[136:137]
	ds_read_b128 v[188:191], v151 offset:32768
	ds_read_b128 v[192:195], v151 offset:33792
	ds_read_b128 v[196:199], v151 offset:34816
	ds_read_b128 v[200:203], v151 offset:35840
	ds_read_b128 v[204:207], v151 offset:36864
	ds_read_b128 v[208:211], v151 offset:37888
	ds_read_b128 v[212:215], v151 offset:38912
	ds_read_b128 v[216:219], v151 offset:39936
	global_load_lds_dwordx4 v[226:227], off
	s_mov_b32 m0, s34
	v_lshl_add_u64 v[226:227], s[26:27], 0, v[132:133]
	global_load_lds_dwordx4 v[226:227], off
	s_waitcnt vmcnt(8) lgkmcnt(0)
	s_setprio 1
	s_barrier
	v_mfma_f32_16x16x32_bf16 v[126:129], v[156:159], v[188:191], v[126:129]
	v_mfma_f32_16x16x32_bf16 v[122:125], v[164:167], v[188:191], v[122:125]
	v_mfma_f32_16x16x32_bf16 v[118:121], v[156:159], v[196:199], v[118:121]
	v_mfma_f32_16x16x32_bf16 v[110:113], v[164:167], v[196:199], v[110:113]
	v_mfma_f32_16x16x32_bf16 v[102:105], v[156:159], v[204:207], v[102:105]
	v_mfma_f32_16x16x32_bf16 v[94:97], v[164:167], v[204:207], v[94:97]
	v_mfma_f32_16x16x32_bf16 v[86:89], v[156:159], v[212:215], v[86:89]
	v_mfma_f32_16x16x32_bf16 v[78:81], v[164:167], v[212:215], v[78:81]
	v_mfma_f32_16x16x32_bf16 v[126:129], v[160:163], v[192:195], v[126:129]
	v_mfma_f32_16x16x32_bf16 v[122:125], v[168:171], v[192:195], v[122:125]
	v_mfma_f32_16x16x32_bf16 v[118:121], v[160:163], v[200:203], v[118:121]
	v_mfma_f32_16x16x32_bf16 v[110:113], v[168:171], v[200:203], v[110:113]
	v_mfma_f32_16x16x32_bf16 v[102:105], v[160:163], v[208:211], v[102:105]
	v_mfma_f32_16x16x32_bf16 v[94:97], v[168:171], v[208:211], v[94:97]
	v_mfma_f32_16x16x32_bf16 v[86:89], v[160:163], v[216:219], v[86:89]
	v_mfma_f32_16x16x32_bf16 v[78:81], v[168:171], v[216:219], v[78:81]
	s_setprio 0
	s_setprio 1
	v_mfma_f32_16x16x32_bf16 v[114:117], v[172:175], v[188:191], v[114:117]
	v_mfma_f32_16x16x32_bf16 v[106:109], v[180:183], v[188:191], v[106:109]
	v_mfma_f32_16x16x32_bf16 v[98:101], v[172:175], v[196:199], v[98:101]
	v_mfma_f32_16x16x32_bf16 v[90:93], v[180:183], v[196:199], v[90:93]
	v_mfma_f32_16x16x32_bf16 v[82:85], v[172:175], v[204:207], v[82:85]
	v_mfma_f32_16x16x32_bf16 v[74:77], v[180:183], v[204:207], v[74:77]
	v_mfma_f32_16x16x32_bf16 v[70:73], v[172:175], v[212:215], v[70:73]
	v_mfma_f32_16x16x32_bf16 v[66:69], v[180:183], v[212:215], v[66:69]
	v_mfma_f32_16x16x32_bf16 v[114:117], v[176:179], v[192:195], v[114:117]
	v_mfma_f32_16x16x32_bf16 v[106:109], v[184:187], v[192:195], v[106:109]
	v_mfma_f32_16x16x32_bf16 v[98:101], v[176:179], v[200:203], v[98:101]
	v_mfma_f32_16x16x32_bf16 v[90:93], v[184:187], v[200:203], v[90:93]
	v_mfma_f32_16x16x32_bf16 v[82:85], v[176:179], v[208:211], v[82:85]
	v_mfma_f32_16x16x32_bf16 v[74:77], v[184:187], v[208:211], v[74:77]
	v_mfma_f32_16x16x32_bf16 v[70:73], v[176:179], v[216:219], v[70:73]
	v_mfma_f32_16x16x32_bf16 v[66:69], v[184:187], v[216:219], v[66:69]
	s_setprio 0
	s_barrier
; #define PG8_STAGE(bufoff, gbase, voff) do { _Pragma("unroll") for (int _i = 0; _i < 2; ++_i) \
;         __builtin_amdgcn_global_load_lds((const unsigned*)((const char*)(gbase) + (voff)[_i]), (LAS unsigned*)(lds + (bufoff) + ldsw + _i * 8192), 16, 0, 0); } while (0)
; #define PG8_LDA(dst, b, h) do { _Pragma("unroll") for (int m = 0; m < 4; ++m) _Pragma("unroll") for (int k = 0; k < 2; ++k) dst[m][k] = *(const LAS bf16x8*)(lds + PG8_SA(b, h) + aoff + m * 2048 + k * 1024); } while (0)
; #define PG8_MMA(ai, bj, At, Bt) do { __builtin_amdgcn_s_setprio(1); _Pragma("unroll") for (int m = 0; m < 4; ++m) _Pragma("unroll") for (int n = 0; n < 2; ++n) _Pragma("unroll") for (int k = 0; k < 2; ++k) \
;         acc[ai][bj][m][n] = __builtin_amdgcn_mfma_f32_16x16x32_bf16(Bt[n][k], At[m][k], acc[ai][bj][m][n], 0, 0, 0); __builtin_amdgcn_s_setprio(0); } while (0)
; #define PG8_WAIT_V(n) asm volatile("s_waitcnt vmcnt(" #n ")" ::: "memory")
; #define PG8_WAIT_L(n) asm volatile("s_waitcnt lgkmcnt(" #n ")" ::: "memory")
; #define PG8_BAR __builtin_amdgcn_s_barrier()
; #define PG8_SCHED __builtin_amdgcn_sched_barrier(0)
; template <class Epi, class Sched, bool ALIGN_EPI = false, bool SP2 = false>
; __device__ __forceinline__ void gemm_phase(LAS unsigned char* lds, const Gemm g, const Sched& S, const Epi& E) {
;     ...
;             PG8_LDA(At, 1, 1); PG8_STAGE(PG8_SB(1, 0), b3, voffB); PG8_STAGE(PG8_SB(1, 1), b3 + hstepB, voffB); PG8_STAGE(PG8_SA(1, 0), a3, voffA);
;             PG8_WAIT_V(8); PG8_WAIT_L(0); PG8_BAR; PG8_MMA(1, 0, At, B0); PG8_MMA(1, 1, At, B1); PG8_BAR; PG8_SCHED;
;     ...
;         if constexpr (ALIGN_EPI) { if (wr == 0) PG8_BAR; }
	s_add_i32 s26, s44, s28
	v_lshl_add_u64 v[146:147], v[146:147], 0, s[6:7]
	s_mov_b32 m0, s26
	ds_read_b128 v[188:191], v151 offset:49152
	ds_read_b128 v[192:195], v151 offset:50176
	ds_read_b128 v[196:199], v151 offset:51200
	ds_read_b128 v[200:203], v151 offset:52224
	ds_read_b128 v[204:207], v151 offset:53248
	ds_read_b128 v[208:211], v151 offset:54272
	ds_read_b128 v[212:215], v151 offset:55296
	ds_read_b128 v[216:219], v151 offset:56320
	global_load_lds_dwordx4 v[146:147], off
	s_add_i32 m0, s26, 0x2000
	s_add_u32 s24, s24, 0x80080
	v_lshl_add_u64 v[146:147], v[220:221], 0, s[6:7]
	s_addc_u32 s25, s25, 0
	s_add_i32 s26, s45, s28
	global_load_lds_dwordx4 v[146:147], off
	s_mov_b32 m0, s26
	v_lshl_add_u64 v[146:147], s[24:25], 0, v[134:135]
	global_load_lds_dwordx4 v[146:147], off
	s_add_i32 m0, s26, 0x2000
	v_lshl_add_u64 v[146:147], s[24:25], 0, v[130:131]
	global_load_lds_dwordx4 v[146:147], off
	s_mov_b32 m0, s36
	v_lshl_add_u64 v[146:147], v[222:223], 0, s[6:7]
	global_load_lds_dwordx4 v[146:147], off
	s_mov_b32 m0, s37
	v_lshl_add_u64 v[146:147], v[224:225], 0, s[6:7]
	global_load_lds_dwordx4 v[146:147], off
	s_waitcnt vmcnt(8) lgkmcnt(0)
	s_setprio 1
	s_barrier
	v_mfma_f32_16x16x32_bf16 v[62:65], v[156:159], v[188:191], v[62:65]
	v_mfma_f32_16x16x32_bf16 v[58:61], v[164:167], v[188:191], v[58:61]
	v_mfma_f32_16x16x32_bf16 v[54:57], v[156:159], v[196:199], v[54:57]
	v_mfma_f32_16x16x32_bf16 v[46:49], v[164:167], v[196:199], v[46:49]
	v_mfma_f32_16x16x32_bf16 v[38:41], v[156:159], v[204:207], v[38:41]
	v_mfma_f32_16x16x32_bf16 v[30:33], v[164:167], v[204:207], v[30:33]
	v_mfma_f32_16x16x32_bf16 v[22:25], v[156:159], v[212:215], v[22:25]
	v_mfma_f32_16x16x32_bf16 v[14:17], v[164:167], v[212:215], v[14:17]
	v_mfma_f32_16x16x32_bf16 v[62:65], v[160:163], v[192:195], v[62:65]
	v_mfma_f32_16x16x32_bf16 v[58:61], v[168:171], v[192:195], v[58:61]
	v_mfma_f32_16x16x32_bf16 v[54:57], v[160:163], v[200:203], v[54:57]
	v_mfma_f32_16x16x32_bf16 v[46:49], v[168:171], v[200:203], v[46:49]
	v_mfma_f32_16x16x32_bf16 v[38:41], v[160:163], v[208:211], v[38:41]
	v_mfma_f32_16x16x32_bf16 v[30:33], v[168:171], v[208:211], v[30:33]
	v_mfma_f32_16x16x32_bf16 v[22:25], v[160:163], v[216:219], v[22:25]
	v_mfma_f32_16x16x32_bf16 v[14:17], v[168:171], v[216:219], v[14:17]
	s_setprio 0
	s_setprio 1
	v_mfma_f32_16x16x32_bf16 v[50:53], v[172:175], v[188:191], v[50:53]
	v_mfma_f32_16x16x32_bf16 v[42:45], v[180:183], v[188:191], v[42:45]
	v_mfma_f32_16x16x32_bf16 v[34:37], v[172:175], v[196:199], v[34:37]
	v_mfma_f32_16x16x32_bf16 v[26:29], v[180:183], v[196:199], v[26:29]
	v_mfma_f32_16x16x32_bf16 v[18:21], v[172:175], v[204:207], v[18:21]
	v_mfma_f32_16x16x32_bf16 v[10:13], v[180:183], v[204:207], v[10:13]
	v_mfma_f32_16x16x32_bf16 v[6:9], v[172:175], v[212:215], v[6:9]
	v_mfma_f32_16x16x32_bf16 v[2:5], v[180:183], v[212:215], v[2:5]
	v_mfma_f32_16x16x32_bf16 v[50:53], v[176:179], v[192:195], v[50:53]
	v_mfma_f32_16x16x32_bf16 v[42:45], v[184:187], v[192:195], v[42:45]
	v_mfma_f32_16x16x32_bf16 v[34:37], v[176:179], v[200:203], v[34:37]
	v_mfma_f32_16x16x32_bf16 v[26:29], v[184:187], v[200:203], v[26:29]
	v_mfma_f32_16x16x32_bf16 v[18:21], v[176:179], v[208:211], v[18:21]
	v_mfma_f32_16x16x32_bf16 v[10:13], v[184:187], v[208:211], v[10:13]
	v_mfma_f32_16x16x32_bf16 v[6:9], v[176:179], v[216:219], v[6:9]
	v_mfma_f32_16x16x32_bf16 v[2:5], v[184:187], v[216:219], v[2:5]
	s_add_i32 s58, s58, 2
	s_add_u32 s22, s22, 0x100
	s_addc_u32 s23, s23, 0
	s_add_u32 s51, s51, 0x100
	s_addc_u32 s55, s55, 0
	s_setprio 0
	s_barrier
	s_cmp_gt_u32 s58, 29
	s_cbranch_scc0 .LBB0_349
	s_and_b64 vcc, exec, s[10:11]
	s_cbranch_vccz .LBB0_352
	s_barrier

; #define PG8_STAGE(bufoff, gbase, voff) do { _Pragma("unroll") for (int _i = 0; _i < 2; ++_i) \
;         __builtin_amdgcn_global_load_lds((const unsigned*)((const char*)(gbase) + (voff)[_i]), (LAS unsigned*)(lds + (bufoff) + ldsw + _i * 8192), 16, 0, 0); } while (0)
; #define PG8_LDA(dst, b, h) do { _Pragma("unroll") for (int m = 0; m < 4; ++m) _Pragma("unroll") for (int k = 0; k < 2; ++k) dst[m][k] = *(const LAS bf16x8*)(lds + PG8_SA(b, h) + aoff + m * 2048 + k * 1024); } while (0)
; #define PG8_LDB(dst, b, h) do { _Pragma("unroll") for (int n = 0; n < 2; ++n) _Pragma("unroll") for (int k = 0; k < 2; ++k) dst[n][k] = *(const LAS bf16x8*)(lds + PG8_SB(b, h) + boff + n * 2048 + k * 1024); } while (0)
; #define PG8_MMA(ai, bj, At, Bt) do { __builtin_amdgcn_s_setprio(1); _Pragma("unroll") for (int m = 0; m < 4; ++m) _Pragma("unroll") for (int n = 0; n < 2; ++n) _Pragma("unroll") for (int k = 0; k < 2; ++k) \
;         acc[ai][bj][m][n] = __builtin_amdgcn_mfma_f32_16x16x32_bf16(Bt[n][k], At[m][k], acc[ai][bj][m][n], 0, 0, 0); __builtin_amdgcn_s_setprio(0); } while (0)
; #define PG8_WAIT_V(n) asm volatile("s_waitcnt vmcnt(" #n ")" ::: "memory")
; #define PG8_WAIT_L(n) asm volatile("s_waitcnt lgkmcnt(" #n ")" ::: "memory")
; template <class Epi, class Sched, bool ALIGN_EPI = false, bool SP2 = false>
; __device__ __forceinline__ void gemm_phase(LAS unsigned char* lds, const Gemm g, const Sched& S, const Epi& E) {
;     ...
;         for (int t = 0; t < nt; t += 2) {
;             const bool last = (t == nt - 2);
;             const char* a1 = cA + (size_t)(t + 1) * kstep;
;             const char* a2 = last ? nA : cA + (size_t)(t + 2) * kstep; const char* b2 = last ? nB : cB + (size_t)(t + 2) * kstep;
;             const char* a3 = a2 + kstep; const char* b3 = b2 + kstep;
;             if (last && has_next) S.a_ready(nxt);
;             if constexpr (SP2) {
;             PG8_LDB(B0, 0, 0); PG8_LDB(B1, 0, 1); PG8_SCHED; PG8_LDA(At, 0, 0); PG8_STAGE(PG8_SA(1, 1), a1 + hstepA, voffA);
;             PG8_WAIT_V(8); PG8_WAIT_L(0); PG8_BAR; PG8_MMA(0, 0, At, B0); PG8_MMA(0, 1, At, B1); PG8_BAR; PG8_SCHED;
;             PG8_LDA(At, 0, 1); PG8_STAGE(PG8_SB(0, 0), b2, voffB); PG8_STAGE(PG8_SB(0, 1), b2 + hstepB, voffB); PG8_STAGE(PG8_SA(0, 0), a2, voffA);
;             PG8_WAIT_V(8); PG8_WAIT_L(0); PG8_BAR; PG8_MMA(1, 0, At, B0); PG8_MMA(1, 1, At, B1); PG8_BAR; PG8_SCHED;
.LBB0_560:
	s_add_u32 s27, s20, s26
	s_addc_u32 s34, s21, 0
	s_add_u32 s30, s27, 0x100
	s_addc_u32 s31, s34, 0
	s_and_b64 s[28:29], s[24:25], exec
	s_cselect_b32 s29, s1, s31
	s_cselect_b32 s28, s0, s30
	s_add_u32 s26, s16, s26
	s_addc_u32 s30, s17, 0
	s_add_u32 s26, s26, 0x100
	s_addc_u32 s30, s30, 0
	s_and_b64 s[24:25], s[24:25], exec
	s_cselect_b32 s31, s19, s30
	s_cselect_b32 s30, s18, s26
	s_add_u32 s36, s27, 0x18080
	ds_read_b128 v[154:157], v147
	ds_read_b128 v[158:161], v147 offset:1024
	ds_read_b128 v[162:165], v147 offset:2048
	ds_read_b128 v[166:169], v147 offset:3072
	ds_read_b128 v[170:173], v148
	ds_read_b128 v[174:177], v148 offset:1024
	ds_read_b128 v[178:181], v148 offset:2048
	ds_read_b128 v[182:185], v148 offset:3072
	s_addc_u32 s37, s34, 0
	s_add_i32 s73, s54, s39
	s_add_i32 m0, s40, 0xc000
	s_add_i32 s76, s40, 0xe000
	s_add_i32 s70, s73, 0x2000
	s_add_u32 s34, s30, 0x18000
	s_addc_u32 s35, s31, 0
	s_add_i32 s72, s55, s39
	s_add_i32 s71, s72, 0x2000
	s_add_u32 s26, s28, 0x18000
	s_addc_u32 s27, s29, 0
	s_add_i32 s67, s57, s39
	s_add_i32 s65, s67, 0x2000
	s_add_u32 s24, s30, 0x18080
	s_addc_u32 s25, s31, 0
	s_add_i32 s66, s58, s39
	s_add_i32 s63, s66, 0x2000
	v_lshl_add_u64 v[218:219], s[36:37], 0, v[130:131]
	ds_read_b128 v[186:189], v149
	ds_read_b128 v[190:193], v149 offset:1024
	ds_read_b128 v[194:197], v149 offset:2048
	ds_read_b128 v[198:201], v149 offset:3072
	ds_read_b128 v[202:205], v149 offset:4096
	ds_read_b128 v[206:209], v149 offset:5120
	ds_read_b128 v[210:213], v149 offset:6144
	ds_read_b128 v[214:217], v149 offset:7168
	global_load_lds_dwordx4 v[218:219], off
	s_mov_b32 m0, s76
	v_lshl_add_u64 v[218:219], s[36:37], 0, v[134:135]
	global_load_lds_dwordx4 v[218:219], off
	s_waitcnt vmcnt(8) lgkmcnt(0)
	s_setprio 1
	s_barrier
	v_mfma_f32_16x16x32_bf16 v[126:129], v[154:157], v[186:189], v[126:129]
	v_mfma_f32_16x16x32_bf16 v[122:125], v[162:165], v[186:189], v[122:125]
	v_mfma_f32_16x16x32_bf16 v[118:121], v[154:157], v[194:197], v[118:121]
	v_mfma_f32_16x16x32_bf16 v[110:113], v[162:165], v[194:197], v[110:113]
	v_mfma_f32_16x16x32_bf16 v[102:105], v[154:157], v[202:205], v[102:105]
	v_mfma_f32_16x16x32_bf16 v[94:97], v[162:165], v[202:205], v[94:97]
	v_mfma_f32_16x16x32_bf16 v[86:89], v[154:157], v[210:213], v[86:89]
	v_mfma_f32_16x16x32_bf16 v[78:81], v[162:165], v[210:213], v[78:81]
	v_mfma_f32_16x16x32_bf16 v[126:129], v[158:161], v[190:193], v[126:129]
	v_mfma_f32_16x16x32_bf16 v[122:125], v[166:169], v[190:193], v[122:125]
	v_mfma_f32_16x16x32_bf16 v[118:121], v[158:161], v[198:201], v[118:121]
	v_mfma_f32_16x16x32_bf16 v[110:113], v[166:169], v[198:201], v[110:113]
	v_mfma_f32_16x16x32_bf16 v[102:105], v[158:161], v[206:209], v[102:105]
	v_mfma_f32_16x16x32_bf16 v[94:97], v[166:169], v[206:209], v[94:97]
	v_mfma_f32_16x16x32_bf16 v[86:89], v[158:161], v[214:217], v[86:89]
	v_mfma_f32_16x16x32_bf16 v[78:81], v[166:169], v[214:217], v[78:81]
	s_setprio 0
	s_setprio 1
	v_mfma_f32_16x16x32_bf16 v[114:117], v[170:173], v[186:189], v[114:117]
	v_mfma_f32_16x16x32_bf16 v[106:109], v[178:181], v[186:189], v[106:109]
	v_mfma_f32_16x16x32_bf16 v[98:101], v[170:173], v[194:197], v[98:101]
	v_mfma_f32_16x16x32_bf16 v[90:93], v[178:181], v[194:197], v[90:93]
	v_mfma_f32_16x16x32_bf16 v[82:85], v[170:173], v[202:205], v[82:85]
	v_mfma_f32_16x16x32_bf16 v[74:77], v[178:181], v[202:205], v[74:77]
	v_mfma_f32_16x16x32_bf16 v[70:73], v[170:173], v[210:213], v[70:73]
	v_mfma_f32_16x16x32_bf16 v[66:69], v[178:181], v[210:213], v[66:69]
	v_mfma_f32_16x16x32_bf16 v[114:117], v[174:177], v[190:193], v[114:117]
	v_mfma_f32_16x16x32_bf16 v[106:109], v[182:185], v[190:193], v[106:109]
	v_mfma_f32_16x16x32_bf16 v[98:101], v[174:177], v[198:201], v[98:101]
	v_mfma_f32_16x16x32_bf16 v[90:93], v[182:185], v[198:201], v[90:93]
	v_mfma_f32_16x16x32_bf16 v[82:85], v[174:177], v[206:209], v[82:85]
	v_mfma_f32_16x16x32_bf16 v[74:77], v[182:185], v[206:209], v[74:77]
	v_mfma_f32_16x16x32_bf16 v[70:73], v[174:177], v[214:217], v[70:73]
	v_mfma_f32_16x16x32_bf16 v[66:69], v[182:185], v[214:217], v[66:69]
	s_setprio 0
	s_barrier
	s_mov_b32 m0, s73
	v_lshl_add_u64 v[218:219], s[30:31], 0, v[132:133]
	ds_read_b128 v[186:189], v149 offset:16384
	ds_read_b128 v[190:193], v149 offset:17408
	ds_read_b128 v[194:197], v149 offset:18432
	ds_read_b128 v[198:201], v149 offset:19456
	ds_read_b128 v[202:205], v149 offset:20480
	ds_read_b128 v[206:209], v149 offset:21504
	ds_read_b128 v[210:213], v149 offset:22528
	ds_read_b128 v[214:217], v149 offset:23552
	global_load_lds_dwordx4 v[218:219], off
	v_lshl_add_u64 v[220:221], s[30:31], 0, v[136:137]
	s_mov_b32 m0, s70
	v_lshl_add_u64 v[222:223], s[34:35], 0, v[132:133]
	global_load_lds_dwordx4 v[220:221], off
	s_mov_b32 m0, s72
	v_lshl_add_u64 v[224:225], s[28:29], 0, v[134:135]
	global_load_lds_dwordx4 v[222:223], off
	s_mov_b32 m0, s71
	v_lshl_add_u64 v[222:223], s[34:35], 0, v[136:137]
	global_load_lds_dwordx4 v[222:223], off
	s_mov_b32 m0, s40
	v_lshl_add_u64 v[222:223], s[28:29], 0, v[130:131]
	global_load_lds_dwordx4 v[222:223], off
	s_mov_b32 m0, s33
	s_nop 0
	global_load_lds_dwordx4 v[224:225], off
	s_waitcnt vmcnt(8) lgkmcnt(0)
	s_setprio 1
	s_barrier
; #define PG8_STAGE(bufoff, gbase, voff) do { _Pragma("unroll") for (int _i = 0; _i < 2; ++_i) \
;         __builtin_amdgcn_global_load_lds((const unsigned*)((const char*)(gbase) + (voff)[_i]), (LAS unsigned*)(lds + (bufoff) + ldsw + _i * 8192), 16, 0, 0); } while (0)
; #define PG8_LDA(dst, b, h) do { _Pragma("unroll") for (int m = 0; m < 4; ++m) _Pragma("unroll") for (int k = 0; k < 2; ++k) dst[m][k] = *(const LAS bf16x8*)(lds + PG8_SA(b, h) + aoff + m * 2048 + k * 1024); } while (0)
; #define PG8_LDB(dst, b, h) do { _Pragma("unroll") for (int n = 0; n < 2; ++n) _Pragma("unroll") for (int k = 0; k < 2; ++k) dst[n][k] = *(const LAS bf16x8*)(lds + PG8_SB(b, h) + boff + n * 2048 + k * 1024); } while (0)
; #define PG8_MMA(ai, bj, At, Bt) do { __builtin_amdgcn_s_setprio(1); _Pragma("unroll") for (int m = 0; m < 4; ++m) _Pragma("unroll") for (int n = 0; n < 2; ++n) _Pragma("unroll") for (int k = 0; k < 2; ++k) \
;         acc[ai][bj][m][n] = __builtin_amdgcn_mfma_f32_16x16x32_bf16(Bt[n][k], At[m][k], acc[ai][bj][m][n], 0, 0, 0); __builtin_amdgcn_s_setprio(0); } while (0)
; #define PG8_WAIT_V(n) asm volatile("s_waitcnt vmcnt(" #n ")" ::: "memory")
; #define PG8_WAIT_L(n) asm volatile("s_waitcnt lgkmcnt(" #n ")" ::: "memory")
; #define PG8_BAR __builtin_amdgcn_s_barrier()
; #define PG8_SCHED __builtin_amdgcn_sched_barrier(0)
; template <class Epi, class Sched, bool ALIGN_EPI = false, bool SP2 = false>
; __device__ __forceinline__ void gemm_phase(LAS unsigned char* lds, const Gemm g, const Sched& S, const Epi& E) {
;     ...
;             PG8_WAIT_V(8); PG8_WAIT_L(0); PG8_BAR; PG8_MMA(1, 0, At, B0); PG8_MMA(1, 1, At, B1); PG8_BAR; PG8_SCHED;
;             PG8_LDB(B0, 1, 0); PG8_LDB(B1, 1, 1); PG8_SCHED; PG8_LDA(At, 1, 0); PG8_STAGE(PG8_SA(0, 1), a2 + hstepA, voffA);
;             PG8_WAIT_V(8); PG8_WAIT_L(0); PG8_BAR; PG8_MMA(0, 0, At, B0); PG8_MMA(0, 1, At, B1); PG8_BAR; PG8_SCHED;
	v_mfma_f32_16x16x32_bf16 v[62:65], v[154:157], v[186:189], v[62:65]
	v_mfma_f32_16x16x32_bf16 v[58:61], v[162:165], v[186:189], v[58:61]
	v_mfma_f32_16x16x32_bf16 v[54:57], v[154:157], v[194:197], v[54:57]
	v_mfma_f32_16x16x32_bf16 v[46:49], v[162:165], v[194:197], v[46:49]
	v_mfma_f32_16x16x32_bf16 v[38:41], v[154:157], v[202:205], v[38:41]
	v_mfma_f32_16x16x32_bf16 v[30:33], v[162:165], v[202:205], v[30:33]
	v_mfma_f32_16x16x32_bf16 v[22:25], v[154:157], v[210:213], v[22:25]
	v_mfma_f32_16x16x32_bf16 v[14:17], v[162:165], v[210:213], v[14:17]
	v_mfma_f32_16x16x32_bf16 v[62:65], v[158:161], v[190:193], v[62:65]
	v_mfma_f32_16x16x32_bf16 v[58:61], v[166:169], v[190:193], v[58:61]
	v_mfma_f32_16x16x32_bf16 v[54:57], v[158:161], v[198:201], v[54:57]
	v_mfma_f32_16x16x32_bf16 v[46:49], v[166:169], v[198:201], v[46:49]
	v_mfma_f32_16x16x32_bf16 v[38:41], v[158:161], v[206:209], v[38:41]
	v_mfma_f32_16x16x32_bf16 v[30:33], v[166:169], v[206:209], v[30:33]
	v_mfma_f32_16x16x32_bf16 v[22:25], v[158:161], v[214:217], v[22:25]
	v_mfma_f32_16x16x32_bf16 v[14:17], v[166:169], v[214:217], v[14:17]
	s_setprio 0
	s_setprio 1
	v_mfma_f32_16x16x32_bf16 v[50:53], v[170:173], v[186:189], v[50:53]
	v_mfma_f32_16x16x32_bf16 v[42:45], v[178:181], v[186:189], v[42:45]
	v_mfma_f32_16x16x32_bf16 v[34:37], v[170:173], v[194:197], v[34:37]
	v_mfma_f32_16x16x32_bf16 v[26:29], v[178:181], v[194:197], v[26:29]
	v_mfma_f32_16x16x32_bf16 v[18:21], v[170:173], v[202:205], v[18:21]
	v_mfma_f32_16x16x32_bf16 v[10:13], v[178:181], v[202:205], v[10:13]
	v_mfma_f32_16x16x32_bf16 v[6:9], v[170:173], v[210:213], v[6:9]
	v_mfma_f32_16x16x32_bf16 v[2:5], v[178:181], v[210:213], v[2:5]
	v_mfma_f32_16x16x32_bf16 v[50:53], v[174:177], v[190:193], v[50:53]
	v_mfma_f32_16x16x32_bf16 v[42:45], v[182:185], v[190:193], v[42:45]
	v_mfma_f32_16x16x32_bf16 v[34:37], v[174:177], v[198:201], v[34:37]
	v_mfma_f32_16x16x32_bf16 v[26:29], v[182:185], v[198:201], v[26:29]
	v_mfma_f32_16x16x32_bf16 v[18:21], v[174:177], v[206:209], v[18:21]
	v_mfma_f32_16x16x32_bf16 v[10:13], v[182:185], v[206:209], v[10:13]
	v_mfma_f32_16x16x32_bf16 v[6:9], v[174:177], v[214:217], v[6:9]
	v_mfma_f32_16x16x32_bf16 v[2:5], v[182:185], v[214:217], v[2:5]
	s_setprio 0
	s_barrier
	ds_read_b128 v[154:157], v150
	ds_read_b128 v[158:161], v150 offset:1024
	ds_read_b128 v[162:165], v150 offset:2048
	ds_read_b128 v[166:169], v150 offset:3072
	ds_read_b128 v[170:173], v151
	ds_read_b128 v[174:177], v151 offset:1024
	ds_read_b128 v[178:181], v151 offset:2048
	ds_read_b128 v[182:185], v151 offset:3072
	s_mov_b32 m0, s41
	v_lshl_add_u64 v[226:227], s[26:27], 0, v[130:131]
	ds_read_b128 v[186:189], v149 offset:32768
	ds_read_b128 v[190:193], v149 offset:33792
	ds_read_b128 v[194:197], v149 offset:34816
	ds_read_b128 v[198:201], v149 offset:35840
	ds_read_b128 v[202:205], v149 offset:36864
	ds_read_b128 v[206:209], v149 offset:37888
	ds_read_b128 v[210:213], v149 offset:38912
	ds_read_b128 v[214:217], v149 offset:39936
	global_load_lds_dwordx4 v[226:227], off
	s_mov_b32 m0, s44
	v_lshl_add_u64 v[226:227], s[26:27], 0, v[134:135]
	global_load_lds_dwordx4 v[226:227], off
	s_waitcnt vmcnt(8) lgkmcnt(0)
	s_setprio 1
	s_barrier
	v_mfma_f32_16x16x32_bf16 v[126:129], v[154:157], v[186:189], v[126:129]
	v_mfma_f32_16x16x32_bf16 v[122:125], v[162:165], v[186:189], v[122:125]
	v_mfma_f32_16x16x32_bf16 v[118:121], v[154:157], v[194:197], v[118:121]
	v_mfma_f32_16x16x32_bf16 v[110:113], v[162:165], v[194:197], v[110:113]
	v_mfma_f32_16x16x32_bf16 v[102:105], v[154:157], v[202:205], v[102:105]
	v_mfma_f32_16x16x32_bf16 v[94:97], v[162:165], v[202:205], v[94:97]
	v_mfma_f32_16x16x32_bf16 v[86:89], v[154:157], v[210:213], v[86:89]
	v_mfma_f32_16x16x32_bf16 v[78:81], v[162:165], v[210:213], v[78:81]
	v_mfma_f32_16x16x32_bf16 v[126:129], v[158:161], v[190:193], v[126:129]
	v_mfma_f32_16x16x32_bf16 v[122:125], v[166:169], v[190:193], v[122:125]
	v_mfma_f32_16x16x32_bf16 v[118:121], v[158:161], v[198:201], v[118:121]
	v_mfma_f32_16x16x32_bf16 v[110:113], v[166:169], v[198:201], v[110:113]
	v_mfma_f32_16x16x32_bf16 v[102:105], v[158:161], v[206:209], v[102:105]
	v_mfma_f32_16x16x32_bf16 v[94:97], v[166:169], v[206:209], v[94:97]
	v_mfma_f32_16x16x32_bf16 v[86:89], v[158:161], v[214:217], v[86:89]
	v_mfma_f32_16x16x32_bf16 v[78:81], v[166:169], v[214:217], v[78:81]
	s_setprio 0
	s_setprio 1
	v_mfma_f32_16x16x32_bf16 v[114:117], v[170:173], v[186:189], v[114:117]
	v_mfma_f32_16x16x32_bf16 v[106:109], v[178:181], v[186:189], v[106:109]
	v_mfma_f32_16x16x32_bf16 v[98:101], v[170:173], v[194:197], v[98:101]
	v_mfma_f32_16x16x32_bf16 v[90:93], v[178:181], v[194:197], v[90:93]
	v_mfma_f32_16x16x32_bf16 v[82:85], v[170:173], v[202:205], v[82:85]
	v_mfma_f32_16x16x32_bf16 v[74:77], v[178:181], v[202:205], v[74:77]
	v_mfma_f32_16x16x32_bf16 v[70:73], v[170:173], v[210:213], v[70:73]
	v_mfma_f32_16x16x32_bf16 v[66:69], v[178:181], v[210:213], v[66:69]
	v_mfma_f32_16x16x32_bf16 v[114:117], v[174:177], v[190:193], v[114:117]
	v_mfma_f32_16x16x32_bf16 v[106:109], v[182:185], v[190:193], v[106:109]
	v_mfma_f32_16x16x32_bf16 v[98:101], v[174:177], v[198:201], v[98:101]
	v_mfma_f32_16x16x32_bf16 v[90:93], v[182:185], v[198:201], v[90:93]
	v_mfma_f32_16x16x32_bf16 v[82:85], v[174:177], v[206:209], v[82:85]
	v_mfma_f32_16x16x32_bf16 v[74:77], v[182:185], v[206:209], v[74:77]
	v_mfma_f32_16x16x32_bf16 v[70:73], v[174:177], v[214:217], v[70:73]
	v_mfma_f32_16x16x32_bf16 v[66:69], v[182:185], v[214:217], v[66:69]
	s_setprio 0
	s_barrier
; #define PG8_STAGE(bufoff, gbase, voff) do { _Pragma("unroll") for (int _i = 0; _i < 2; ++_i) \
;         __builtin_amdgcn_global_load_lds((const unsigned*)((const char*)(gbase) + (voff)[_i]), (LAS unsigned*)(lds + (bufoff) + ldsw + _i * 8192), 16, 0, 0); } while (0)
; #define PG8_LDA(dst, b, h) do { _Pragma("unroll") for (int m = 0; m < 4; ++m) _Pragma("unroll") for (int k = 0; k < 2; ++k) dst[m][k] = *(const LAS bf16x8*)(lds + PG8_SA(b, h) + aoff + m * 2048 + k * 1024); } while (0)
; #define PG8_MMA(ai, bj, At, Bt) do { __builtin_amdgcn_s_setprio(1); _Pragma("unroll") for (int m = 0; m < 4; ++m) _Pragma("unroll") for (int n = 0; n < 2; ++n) _Pragma("unroll") for (int k = 0; k < 2; ++k) \
;         acc[ai][bj][m][n] = __builtin_amdgcn_mfma_f32_16x16x32_bf16(Bt[n][k], At[m][k], acc[ai][bj][m][n], 0, 0, 0); __builtin_amdgcn_s_setprio(0); } while (0)
; #define PG8_WAIT_V(n) asm volatile("s_waitcnt vmcnt(" #n ")" ::: "memory")
; #define PG8_WAIT_L(n) asm volatile("s_waitcnt lgkmcnt(" #n ")" ::: "memory")
; #define PG8_BAR __builtin_amdgcn_s_barrier()
; #define PG8_SCHED __builtin_amdgcn_sched_barrier(0)
; template <class Epi, class Sched, bool ALIGN_EPI = false, bool SP2 = false>
; __device__ __forceinline__ void gemm_phase(LAS unsigned char* lds, const Gemm g, const Sched& S, const Epi& E) {
;     ...
;             PG8_LDA(At, 1, 1); PG8_STAGE(PG8_SB(1, 0), b3, voffB); PG8_STAGE(PG8_SB(1, 1), b3 + hstepB, voffB); PG8_STAGE(PG8_SA(1, 0), a3, voffA);
;             PG8_WAIT_V(8); PG8_WAIT_L(0); PG8_BAR; PG8_MMA(1, 0, At, B0); PG8_MMA(1, 1, At, B1); PG8_BAR; PG8_SCHED;
;     ...
;         if constexpr (ALIGN_EPI) { if (wr == 0) PG8_BAR; }
	s_mov_b32 m0, s67
	v_lshl_add_u64 v[218:219], v[218:219], 0, s[12:13]
	ds_read_b128 v[186:189], v149 offset:49152
	ds_read_b128 v[190:193], v149 offset:50176
	ds_read_b128 v[194:197], v149 offset:51200
	ds_read_b128 v[198:201], v149 offset:52224
	ds_read_b128 v[202:205], v149 offset:53248
	ds_read_b128 v[206:209], v149 offset:54272
	ds_read_b128 v[210:213], v149 offset:55296
	ds_read_b128 v[214:217], v149 offset:56320
	global_load_lds_dwordx4 v[218:219], off
	s_mov_b32 m0, s65
	v_lshl_add_u64 v[218:219], v[220:221], 0, s[12:13]
	global_load_lds_dwordx4 v[218:219], off
	s_mov_b32 m0, s66
	v_lshl_add_u64 v[218:219], s[24:25], 0, v[132:133]
	global_load_lds_dwordx4 v[218:219], off
	s_mov_b32 m0, s63
	v_lshl_add_u64 v[218:219], s[24:25], 0, v[136:137]
	global_load_lds_dwordx4 v[218:219], off
	s_mov_b32 m0, s45
	v_lshl_add_u64 v[218:219], v[222:223], 0, s[12:13]
	global_load_lds_dwordx4 v[218:219], off
	s_mov_b32 m0, s46
	v_lshl_add_u64 v[218:219], v[224:225], 0, s[12:13]
	global_load_lds_dwordx4 v[218:219], off
	s_waitcnt vmcnt(8) lgkmcnt(0)
	s_setprio 1
	s_barrier
	v_mfma_f32_16x16x32_bf16 v[62:65], v[154:157], v[186:189], v[62:65]
	v_mfma_f32_16x16x32_bf16 v[58:61], v[162:165], v[186:189], v[58:61]
	v_mfma_f32_16x16x32_bf16 v[54:57], v[154:157], v[194:197], v[54:57]
	v_mfma_f32_16x16x32_bf16 v[46:49], v[162:165], v[194:197], v[46:49]
	v_mfma_f32_16x16x32_bf16 v[38:41], v[154:157], v[202:205], v[38:41]
	v_mfma_f32_16x16x32_bf16 v[30:33], v[162:165], v[202:205], v[30:33]
	v_mfma_f32_16x16x32_bf16 v[22:25], v[154:157], v[210:213], v[22:25]
	v_mfma_f32_16x16x32_bf16 v[14:17], v[162:165], v[210:213], v[14:17]
	v_mfma_f32_16x16x32_bf16 v[62:65], v[158:161], v[190:193], v[62:65]
	v_mfma_f32_16x16x32_bf16 v[58:61], v[166:169], v[190:193], v[58:61]
	v_mfma_f32_16x16x32_bf16 v[54:57], v[158:161], v[198:201], v[54:57]
	v_mfma_f32_16x16x32_bf16 v[46:49], v[166:169], v[198:201], v[46:49]
	v_mfma_f32_16x16x32_bf16 v[38:41], v[158:161], v[206:209], v[38:41]
	v_mfma_f32_16x16x32_bf16 v[30:33], v[166:169], v[206:209], v[30:33]
	v_mfma_f32_16x16x32_bf16 v[22:25], v[158:161], v[214:217], v[22:25]
	v_mfma_f32_16x16x32_bf16 v[14:17], v[166:169], v[214:217], v[14:17]
	s_setprio 0
	s_setprio 1
	v_mfma_f32_16x16x32_bf16 v[50:53], v[170:173], v[186:189], v[50:53]
	v_mfma_f32_16x16x32_bf16 v[42:45], v[178:181], v[186:189], v[42:45]
	v_mfma_f32_16x16x32_bf16 v[34:37], v[170:173], v[194:197], v[34:37]
	v_mfma_f32_16x16x32_bf16 v[26:29], v[178:181], v[194:197], v[26:29]
	v_mfma_f32_16x16x32_bf16 v[18:21], v[170:173], v[202:205], v[18:21]
	v_mfma_f32_16x16x32_bf16 v[10:13], v[178:181], v[202:205], v[10:13]
	v_mfma_f32_16x16x32_bf16 v[6:9], v[170:173], v[210:213], v[6:9]
	v_mfma_f32_16x16x32_bf16 v[2:5], v[178:181], v[210:213], v[2:5]
	v_mfma_f32_16x16x32_bf16 v[50:53], v[174:177], v[190:193], v[50:53]
	v_mfma_f32_16x16x32_bf16 v[42:45], v[182:185], v[190:193], v[42:45]
	v_mfma_f32_16x16x32_bf16 v[34:37], v[174:177], v[198:201], v[34:37]
	v_mfma_f32_16x16x32_bf16 v[26:29], v[182:185], v[198:201], v[26:29]
	v_mfma_f32_16x16x32_bf16 v[18:21], v[174:177], v[206:209], v[18:21]
	v_mfma_f32_16x16x32_bf16 v[10:13], v[182:185], v[206:209], v[10:13]
	v_mfma_f32_16x16x32_bf16 v[6:9], v[174:177], v[214:217], v[6:9]
	v_mfma_f32_16x16x32_bf16 v[2:5], v[182:185], v[214:217], v[2:5]
	s_setprio 0
	s_barrier
	s_movk_i32 s26, 0x100
	s_andn2_b64 vcc, exec, s[22:23]
	s_mov_b64 s[24:25], -1
	s_mov_b64 s[22:23], 0
	s_cbranch_vccz .LBB0_560
	s_and_b64 vcc, exec, s[14:15]
	s_cbranch_vccz .LBB0_563
	s_barrier

; #define PG8_STAGE(bufoff, gbase, voff) do { _Pragma("unroll") for (int _i = 0; _i < 2; ++_i) \
;         __builtin_amdgcn_global_load_lds((const unsigned*)((const char*)(gbase) + (voff)[_i]), (LAS unsigned*)(lds + (bufoff) + ldsw + _i * 8192), 16, 0, 0); } while (0)
; #define PG8_LDA(dst, b, h) do { _Pragma("unroll") for (int m = 0; m < 4; ++m) _Pragma("unroll") for (int k = 0; k < 2; ++k) dst[m][k] = *(const LAS bf16x8*)(lds + PG8_SA(b, h) + aoff + m * 2048 + k * 1024); } while (0)
; #define PG8_LDB(dst, b, h) do { _Pragma("unroll") for (int n = 0; n < 2; ++n) _Pragma("unroll") for (int k = 0; k < 2; ++k) dst[n][k] = *(const LAS bf16x8*)(lds + PG8_SB(b, h) + boff + n * 2048 + k * 1024); } while (0)
; #define PG8_MMA(ai, bj, At, Bt) do { __builtin_amdgcn_s_setprio(1); _Pragma("unroll") for (int m = 0; m < 4; ++m) _Pragma("unroll") for (int n = 0; n < 2; ++n) _Pragma("unroll") for (int k = 0; k < 2; ++k) \
;         acc[ai][bj][m][n] = __builtin_amdgcn_mfma_f32_16x16x32_bf16(Bt[n][k], At[m][k], acc[ai][bj][m][n], 0, 0, 0); __builtin_amdgcn_s_setprio(0); } while (0)
; #define PG8_BAR __builtin_amdgcn_s_barrier()
; template <class Epi, class Sched, bool ALIGN_EPI = false, bool SP2 = false>
; __device__ __forceinline__ void gemm_phase(LAS unsigned char* lds, const Gemm g, const Sched& S, const Epi& E) {
;     ...
;         const bool has_next = S.next(ui + 1, nxt);
;         const char* nA = has_next ? (const char*)g.A + (size_t)nxt.pm * tstepA : cA; const char* nB = has_next ? (const char*)g.Bt + (size_t)nxt.pn * tstepB : cB;
;         for (int t = 0; t < nt; t += 2) {
;             const bool last = (t == nt - 2);
;             const char* a1 = cA + (size_t)(t + 1) * kstep;
;             const char* a2 = last ? nA : cA + (size_t)(t + 2) * kstep; const char* b2 = last ? nB : cB + (size_t)(t + 2) * kstep;
;             const char* a3 = a2 + kstep; const char* b3 = b2 + kstep;
;             if (last && has_next) S.a_ready(nxt);
;             if constexpr (SP2) {
;             PG8_LDB(B0, 0, 0); PG8_LDB(B1, 0, 1); PG8_SCHED; PG8_LDA(At, 0, 0); PG8_STAGE(PG8_SA(1, 1), a1 + hstepA, voffA);
;             PG8_WAIT_V(8); PG8_WAIT_L(0); PG8_BAR; PG8_MMA(0, 0, At, B0); PG8_MMA(0, 1, At, B1); PG8_BAR; PG8_SCHED;
;             PG8_LDA(At, 0, 1); PG8_STAGE(PG8_SB(0, 0), b2, voffB); PG8_STAGE(PG8_SB(0, 1), b2 + hstepB, voffB); PG8_STAGE(PG8_SA(0, 0), a2, voffA);
.LBB0_588:
	s_add_u32 s27, s20, s26
	s_addc_u32 s34, s21, 0
	s_add_u32 s30, s27, 0x100
	s_addc_u32 s31, s34, 0
	s_and_b64 s[28:29], s[24:25], exec
	s_cselect_b32 s29, s1, s31
	s_cselect_b32 s28, s0, s30
	s_add_u32 s26, s18, s26
	s_addc_u32 s30, s19, 0
	s_add_u32 s26, s26, 0x100
	s_addc_u32 s30, s30, 0
	s_and_b64 s[24:25], s[24:25], exec
	s_cselect_b32 s31, s17, s30
	s_cselect_b32 s30, s16, s26
	s_add_u32 s36, s27, 0x18080
	ds_read_b128 v[148:151], v142
	ds_read_b128 v[154:157], v142 offset:1024
	ds_read_b128 v[158:161], v142 offset:2048
	ds_read_b128 v[162:165], v142 offset:3072
	ds_read_b128 v[166:169], v143
	ds_read_b128 v[170:173], v143 offset:1024
	ds_read_b128 v[174:177], v143 offset:2048
	ds_read_b128 v[178:181], v143 offset:3072
	s_addc_u32 s37, s34, 0
	s_add_i32 s77, s56, s44
	s_add_i32 m0, s45, 0xc000
	s_add_i32 s78, s45, 0xe000
	s_add_i32 s72, s77, 0x2000
	s_add_u32 s34, s30, 0x18000
	s_addc_u32 s35, s31, 0
	s_add_i32 s76, s57, s44
	s_add_i32 s73, s76, 0x2000
	s_add_u32 s26, s28, 0x18000
	s_addc_u32 s27, s29, 0
	s_add_i32 s71, s59, s44
	s_add_i32 s67, s71, 0x2000
	s_add_u32 s24, s30, 0x18080
	s_addc_u32 s25, s31, 0
	s_add_i32 s70, s60, s44
	s_add_i32 s66, s70, 0x2000
	v_lshl_add_u64 v[214:215], s[36:37], 0, v[130:131]
	ds_read_b128 v[182:185], v144
	ds_read_b128 v[186:189], v144 offset:1024
	ds_read_b128 v[190:193], v144 offset:2048
	ds_read_b128 v[194:197], v144 offset:3072
	ds_read_b128 v[198:201], v144 offset:4096
	ds_read_b128 v[202:205], v144 offset:5120
	ds_read_b128 v[206:209], v144 offset:6144
	ds_read_b128 v[210:213], v144 offset:7168
	global_load_lds_dwordx4 v[214:215], off
	s_mov_b32 m0, s78
	v_lshl_add_u64 v[214:215], s[36:37], 0, v[134:135]
	global_load_lds_dwordx4 v[214:215], off
	s_waitcnt vmcnt(8) lgkmcnt(0)
	s_setprio 1
	s_barrier
	v_mfma_f32_16x16x32_bf16 v[126:129], v[148:151], v[182:185], v[126:129]
	v_mfma_f32_16x16x32_bf16 v[122:125], v[158:161], v[182:185], v[122:125]
	v_mfma_f32_16x16x32_bf16 v[118:121], v[148:151], v[190:193], v[118:121]
	v_mfma_f32_16x16x32_bf16 v[110:113], v[158:161], v[190:193], v[110:113]
	v_mfma_f32_16x16x32_bf16 v[102:105], v[148:151], v[198:201], v[102:105]
	v_mfma_f32_16x16x32_bf16 v[94:97], v[158:161], v[198:201], v[94:97]
	v_mfma_f32_16x16x32_bf16 v[86:89], v[148:151], v[206:209], v[86:89]
	v_mfma_f32_16x16x32_bf16 v[78:81], v[158:161], v[206:209], v[78:81]
	v_mfma_f32_16x16x32_bf16 v[126:129], v[154:157], v[186:189], v[126:129]
	v_mfma_f32_16x16x32_bf16 v[122:125], v[162:165], v[186:189], v[122:125]
	v_mfma_f32_16x16x32_bf16 v[118:121], v[154:157], v[194:197], v[118:121]
	v_mfma_f32_16x16x32_bf16 v[110:113], v[162:165], v[194:197], v[110:113]
	v_mfma_f32_16x16x32_bf16 v[102:105], v[154:157], v[202:205], v[102:105]
	v_mfma_f32_16x16x32_bf16 v[94:97], v[162:165], v[202:205], v[94:97]
	v_mfma_f32_16x16x32_bf16 v[86:89], v[154:157], v[210:213], v[86:89]
	v_mfma_f32_16x16x32_bf16 v[78:81], v[162:165], v[210:213], v[78:81]
	s_setprio 0
	s_setprio 1
	v_mfma_f32_16x16x32_bf16 v[114:117], v[166:169], v[182:185], v[114:117]
	v_mfma_f32_16x16x32_bf16 v[106:109], v[174:177], v[182:185], v[106:109]
	v_mfma_f32_16x16x32_bf16 v[98:101], v[166:169], v[190:193], v[98:101]
	v_mfma_f32_16x16x32_bf16 v[90:93], v[174:177], v[190:193], v[90:93]
	v_mfma_f32_16x16x32_bf16 v[82:85], v[166:169], v[198:201], v[82:85]
	v_mfma_f32_16x16x32_bf16 v[74:77], v[174:177], v[198:201], v[74:77]
	v_mfma_f32_16x16x32_bf16 v[70:73], v[166:169], v[206:209], v[70:73]
	v_mfma_f32_16x16x32_bf16 v[66:69], v[174:177], v[206:209], v[66:69]
	v_mfma_f32_16x16x32_bf16 v[114:117], v[170:173], v[186:189], v[114:117]
	v_mfma_f32_16x16x32_bf16 v[106:109], v[178:181], v[186:189], v[106:109]
	v_mfma_f32_16x16x32_bf16 v[98:101], v[170:173], v[194:197], v[98:101]
	v_mfma_f32_16x16x32_bf16 v[90:93], v[178:181], v[194:197], v[90:93]
	v_mfma_f32_16x16x32_bf16 v[82:85], v[170:173], v[202:205], v[82:85]
	v_mfma_f32_16x16x32_bf16 v[74:77], v[178:181], v[202:205], v[74:77]
	v_mfma_f32_16x16x32_bf16 v[70:73], v[170:173], v[210:213], v[70:73]
	v_mfma_f32_16x16x32_bf16 v[66:69], v[178:181], v[210:213], v[66:69]
	s_setprio 0
	s_barrier
	s_mov_b32 m0, s77
	v_lshl_add_u64 v[214:215], s[30:31], 0, v[132:133]
	ds_read_b128 v[182:185], v144 offset:16384
	ds_read_b128 v[186:189], v144 offset:17408
	ds_read_b128 v[190:193], v144 offset:18432
	ds_read_b128 v[194:197], v144 offset:19456
	ds_read_b128 v[198:201], v144 offset:20480
	ds_read_b128 v[202:205], v144 offset:21504
	ds_read_b128 v[206:209], v144 offset:22528
	ds_read_b128 v[210:213], v144 offset:23552
	global_load_lds_dwordx4 v[214:215], off
	v_lshl_add_u64 v[216:217], s[30:31], 0, v[136:137]
	s_mov_b32 m0, s72
	v_lshl_add_u64 v[218:219], s[34:35], 0, v[132:133]
	global_load_lds_dwordx4 v[216:217], off
	s_mov_b32 m0, s76
	v_lshl_add_u64 v[220:221], s[28:29], 0, v[134:135]
	global_load_lds_dwordx4 v[218:219], off
	s_mov_b32 m0, s73
	v_lshl_add_u64 v[218:219], s[34:35], 0, v[136:137]
	global_load_lds_dwordx4 v[218:219], off
	s_mov_b32 m0, s45
	v_lshl_add_u64 v[218:219], s[28:29], 0, v[130:131]
	global_load_lds_dwordx4 v[218:219], off
	s_mov_b32 m0, s46
	s_nop 0
	global_load_lds_dwordx4 v[220:221], off
	s_waitcnt vmcnt(8) lgkmcnt(0)
	s_setprio 1
	s_barrier
; #define PG8_STAGE(bufoff, gbase, voff) do { _Pragma("unroll") for (int _i = 0; _i < 2; ++_i) \
;         __builtin_amdgcn_global_load_lds((const unsigned*)((const char*)(gbase) + (voff)[_i]), (LAS unsigned*)(lds + (bufoff) + ldsw + _i * 8192), 16, 0, 0); } while (0)
; #define PG8_LDA(dst, b, h) do { _Pragma("unroll") for (int m = 0; m < 4; ++m) _Pragma("unroll") for (int k = 0; k < 2; ++k) dst[m][k] = *(const LAS bf16x8*)(lds + PG8_SA(b, h) + aoff + m * 2048 + k * 1024); } while (0)
; #define PG8_LDB(dst, b, h) do { _Pragma("unroll") for (int n = 0; n < 2; ++n) _Pragma("unroll") for (int k = 0; k < 2; ++k) dst[n][k] = *(const LAS bf16x8*)(lds + PG8_SB(b, h) + boff + n * 2048 + k * 1024); } while (0)
; #define PG8_MMA(ai, bj, At, Bt) do { __builtin_amdgcn_s_setprio(1); _Pragma("unroll") for (int m = 0; m < 4; ++m) _Pragma("unroll") for (int n = 0; n < 2; ++n) _Pragma("unroll") for (int k = 0; k < 2; ++k) \
;         acc[ai][bj][m][n] = __builtin_amdgcn_mfma_f32_16x16x32_bf16(Bt[n][k], At[m][k], acc[ai][bj][m][n], 0, 0, 0); __builtin_amdgcn_s_setprio(0); } while (0)
; #define PG8_WAIT_V(n) asm volatile("s_waitcnt vmcnt(" #n ")" ::: "memory")
; #define PG8_WAIT_L(n) asm volatile("s_waitcnt lgkmcnt(" #n ")" ::: "memory")
; #define PG8_BAR __builtin_amdgcn_s_barrier()
; #define PG8_SCHED __builtin_amdgcn_sched_barrier(0)
; template <class Epi, class Sched, bool ALIGN_EPI = false, bool SP2 = false>
; __device__ __forceinline__ void gemm_phase(LAS unsigned char* lds, const Gemm g, const Sched& S, const Epi& E) {
;     ...
;             PG8_WAIT_V(8); PG8_WAIT_L(0); PG8_BAR; PG8_MMA(1, 0, At, B0); PG8_MMA(1, 1, At, B1); PG8_BAR; PG8_SCHED;
;             PG8_LDB(B0, 1, 0); PG8_LDB(B1, 1, 1); PG8_SCHED; PG8_LDA(At, 1, 0); PG8_STAGE(PG8_SA(0, 1), a2 + hstepA, voffA);
;             PG8_WAIT_V(8); PG8_WAIT_L(0); PG8_BAR; PG8_MMA(0, 0, At, B0); PG8_MMA(0, 1, At, B1); PG8_BAR; PG8_SCHED;
	v_mfma_f32_16x16x32_bf16 v[62:65], v[148:151], v[182:185], v[62:65]
	v_mfma_f32_16x16x32_bf16 v[58:61], v[158:161], v[182:185], v[58:61]
	v_mfma_f32_16x16x32_bf16 v[54:57], v[148:151], v[190:193], v[54:57]
	v_mfma_f32_16x16x32_bf16 v[46:49], v[158:161], v[190:193], v[46:49]
	v_mfma_f32_16x16x32_bf16 v[38:41], v[148:151], v[198:201], v[38:41]
	v_mfma_f32_16x16x32_bf16 v[30:33], v[158:161], v[198:201], v[30:33]
	v_mfma_f32_16x16x32_bf16 v[22:25], v[148:151], v[206:209], v[22:25]
	v_mfma_f32_16x16x32_bf16 v[14:17], v[158:161], v[206:209], v[14:17]
	v_mfma_f32_16x16x32_bf16 v[62:65], v[154:157], v[186:189], v[62:65]
	v_mfma_f32_16x16x32_bf16 v[58:61], v[162:165], v[186:189], v[58:61]
	v_mfma_f32_16x16x32_bf16 v[54:57], v[154:157], v[194:197], v[54:57]
	v_mfma_f32_16x16x32_bf16 v[46:49], v[162:165], v[194:197], v[46:49]
	v_mfma_f32_16x16x32_bf16 v[38:41], v[154:157], v[202:205], v[38:41]
	v_mfma_f32_16x16x32_bf16 v[30:33], v[162:165], v[202:205], v[30:33]
	v_mfma_f32_16x16x32_bf16 v[22:25], v[154:157], v[210:213], v[22:25]
	v_mfma_f32_16x16x32_bf16 v[14:17], v[162:165], v[210:213], v[14:17]
	s_setprio 0
	s_setprio 1
	v_mfma_f32_16x16x32_bf16 v[50:53], v[166:169], v[182:185], v[50:53]
	v_mfma_f32_16x16x32_bf16 v[42:45], v[174:177], v[182:185], v[42:45]
	v_mfma_f32_16x16x32_bf16 v[34:37], v[166:169], v[190:193], v[34:37]
	v_mfma_f32_16x16x32_bf16 v[26:29], v[174:177], v[190:193], v[26:29]
	v_mfma_f32_16x16x32_bf16 v[18:21], v[166:169], v[198:201], v[18:21]
	v_mfma_f32_16x16x32_bf16 v[10:13], v[174:177], v[198:201], v[10:13]
	v_mfma_f32_16x16x32_bf16 v[6:9], v[166:169], v[206:209], v[6:9]
	v_mfma_f32_16x16x32_bf16 v[2:5], v[174:177], v[206:209], v[2:5]
	v_mfma_f32_16x16x32_bf16 v[50:53], v[170:173], v[186:189], v[50:53]
	v_mfma_f32_16x16x32_bf16 v[42:45], v[178:181], v[186:189], v[42:45]
	v_mfma_f32_16x16x32_bf16 v[34:37], v[170:173], v[194:197], v[34:37]
	v_mfma_f32_16x16x32_bf16 v[26:29], v[178:181], v[194:197], v[26:29]
	v_mfma_f32_16x16x32_bf16 v[18:21], v[170:173], v[202:205], v[18:21]
	v_mfma_f32_16x16x32_bf16 v[10:13], v[178:181], v[202:205], v[10:13]
	v_mfma_f32_16x16x32_bf16 v[6:9], v[170:173], v[210:213], v[6:9]
	v_mfma_f32_16x16x32_bf16 v[2:5], v[178:181], v[210:213], v[2:5]
	s_setprio 0
	s_barrier
	ds_read_b128 v[148:151], v146
	ds_read_b128 v[154:157], v146 offset:1024
	ds_read_b128 v[158:161], v146 offset:2048
	ds_read_b128 v[162:165], v146 offset:3072
	ds_read_b128 v[166:169], v147
	ds_read_b128 v[170:173], v147 offset:1024
	ds_read_b128 v[174:177], v147 offset:2048
	ds_read_b128 v[178:181], v147 offset:3072
	s_mov_b32 m0, s47
	v_lshl_add_u64 v[222:223], s[26:27], 0, v[130:131]
	ds_read_b128 v[182:185], v144 offset:32768
	ds_read_b128 v[186:189], v144 offset:33792
	ds_read_b128 v[190:193], v144 offset:34816
	ds_read_b128 v[194:197], v144 offset:35840
	ds_read_b128 v[198:201], v144 offset:36864
	ds_read_b128 v[202:205], v144 offset:37888
	ds_read_b128 v[206:209], v144 offset:38912
	ds_read_b128 v[210:213], v144 offset:39936
	global_load_lds_dwordx4 v[222:223], off
	s_mov_b32 m0, s50
	v_lshl_add_u64 v[222:223], s[26:27], 0, v[134:135]
	global_load_lds_dwordx4 v[222:223], off
	s_waitcnt vmcnt(8) lgkmcnt(0)
	s_setprio 1
	s_barrier
	v_mfma_f32_16x16x32_bf16 v[126:129], v[148:151], v[182:185], v[126:129]
	v_mfma_f32_16x16x32_bf16 v[122:125], v[158:161], v[182:185], v[122:125]
	v_mfma_f32_16x16x32_bf16 v[118:121], v[148:151], v[190:193], v[118:121]
	v_mfma_f32_16x16x32_bf16 v[110:113], v[158:161], v[190:193], v[110:113]
	v_mfma_f32_16x16x32_bf16 v[102:105], v[148:151], v[198:201], v[102:105]
	v_mfma_f32_16x16x32_bf16 v[94:97], v[158:161], v[198:201], v[94:97]
	v_mfma_f32_16x16x32_bf16 v[86:89], v[148:151], v[206:209], v[86:89]
	v_mfma_f32_16x16x32_bf16 v[78:81], v[158:161], v[206:209], v[78:81]
	v_mfma_f32_16x16x32_bf16 v[126:129], v[154:157], v[186:189], v[126:129]
	v_mfma_f32_16x16x32_bf16 v[122:125], v[162:165], v[186:189], v[122:125]
	v_mfma_f32_16x16x32_bf16 v[118:121], v[154:157], v[194:197], v[118:121]
	v_mfma_f32_16x16x32_bf16 v[110:113], v[162:165], v[194:197], v[110:113]
	v_mfma_f32_16x16x32_bf16 v[102:105], v[154:157], v[202:205], v[102:105]
	v_mfma_f32_16x16x32_bf16 v[94:97], v[162:165], v[202:205], v[94:97]
	v_mfma_f32_16x16x32_bf16 v[86:89], v[154:157], v[210:213], v[86:89]
	v_mfma_f32_16x16x32_bf16 v[78:81], v[162:165], v[210:213], v[78:81]
	s_setprio 0
	s_setprio 1
	v_mfma_f32_16x16x32_bf16 v[114:117], v[166:169], v[182:185], v[114:117]
	v_mfma_f32_16x16x32_bf16 v[106:109], v[174:177], v[182:185], v[106:109]
	v_mfma_f32_16x16x32_bf16 v[98:101], v[166:169], v[190:193], v[98:101]
	v_mfma_f32_16x16x32_bf16 v[90:93], v[174:177], v[190:193], v[90:93]
	v_mfma_f32_16x16x32_bf16 v[82:85], v[166:169], v[198:201], v[82:85]
	v_mfma_f32_16x16x32_bf16 v[74:77], v[174:177], v[198:201], v[74:77]
	v_mfma_f32_16x16x32_bf16 v[70:73], v[166:169], v[206:209], v[70:73]
	v_mfma_f32_16x16x32_bf16 v[66:69], v[174:177], v[206:209], v[66:69]
	v_mfma_f32_16x16x32_bf16 v[114:117], v[170:173], v[186:189], v[114:117]
	v_mfma_f32_16x16x32_bf16 v[106:109], v[178:181], v[186:189], v[106:109]
	v_mfma_f32_16x16x32_bf16 v[98:101], v[170:173], v[194:197], v[98:101]
	v_mfma_f32_16x16x32_bf16 v[90:93], v[178:181], v[194:197], v[90:93]
	v_mfma_f32_16x16x32_bf16 v[82:85], v[170:173], v[202:205], v[82:85]
	v_mfma_f32_16x16x32_bf16 v[74:77], v[178:181], v[202:205], v[74:77]
	v_mfma_f32_16x16x32_bf16 v[70:73], v[170:173], v[210:213], v[70:73]
	v_mfma_f32_16x16x32_bf16 v[66:69], v[178:181], v[210:213], v[66:69]
	s_setprio 0
	s_barrier
; #define PG8_STAGE(bufoff, gbase, voff) do { _Pragma("unroll") for (int _i = 0; _i < 2; ++_i) \
;         __builtin_amdgcn_global_load_lds((const unsigned*)((const char*)(gbase) + (voff)[_i]), (LAS unsigned*)(lds + (bufoff) + ldsw + _i * 8192), 16, 0, 0); } while (0)
; #define PG8_LDA(dst, b, h) do { _Pragma("unroll") for (int m = 0; m < 4; ++m) _Pragma("unroll") for (int k = 0; k < 2; ++k) dst[m][k] = *(const LAS bf16x8*)(lds + PG8_SA(b, h) + aoff + m * 2048 + k * 1024); } while (0)
; #define PG8_MMA(ai, bj, At, Bt) do { __builtin_amdgcn_s_setprio(1); _Pragma("unroll") for (int m = 0; m < 4; ++m) _Pragma("unroll") for (int n = 0; n < 2; ++n) _Pragma("unroll") for (int k = 0; k < 2; ++k) \
;         acc[ai][bj][m][n] = __builtin_amdgcn_mfma_f32_16x16x32_bf16(Bt[n][k], At[m][k], acc[ai][bj][m][n], 0, 0, 0); __builtin_amdgcn_s_setprio(0); } while (0)
; #define PG8_WAIT_V(n) asm volatile("s_waitcnt vmcnt(" #n ")" ::: "memory")
; #define PG8_WAIT_L(n) asm volatile("s_waitcnt lgkmcnt(" #n ")" ::: "memory")
; #define PG8_BAR __builtin_amdgcn_s_barrier()
; #define PG8_SCHED __builtin_amdgcn_sched_barrier(0)
; template <class Epi, class Sched, bool ALIGN_EPI = false, bool SP2 = false>
; __device__ __forceinline__ void gemm_phase(LAS unsigned char* lds, const Gemm g, const Sched& S, const Epi& E) {
;     ...
;             PG8_LDA(At, 1, 1); PG8_STAGE(PG8_SB(1, 0), b3, voffB); PG8_STAGE(PG8_SB(1, 1), b3 + hstepB, voffB); PG8_STAGE(PG8_SA(1, 0), a3, voffA);
;             PG8_WAIT_V(8); PG8_WAIT_L(0); PG8_BAR; PG8_MMA(1, 0, At, B0); PG8_MMA(1, 1, At, B1); PG8_BAR; PG8_SCHED;
;     ...
;         if constexpr (ALIGN_EPI) { if (wr == 0) PG8_BAR; }
	s_mov_b32 m0, s71
	v_lshl_add_u64 v[214:215], v[214:215], 0, s[12:13]
	ds_read_b128 v[182:185], v144 offset:49152
	ds_read_b128 v[186:189], v144 offset:50176
	ds_read_b128 v[190:193], v144 offset:51200
	ds_read_b128 v[194:197], v144 offset:52224
	ds_read_b128 v[198:201], v144 offset:53248
	ds_read_b128 v[202:205], v144 offset:54272
	ds_read_b128 v[206:209], v144 offset:55296
	ds_read_b128 v[210:213], v144 offset:56320
	global_load_lds_dwordx4 v[214:215], off
	s_mov_b32 m0, s67
	v_lshl_add_u64 v[214:215], v[216:217], 0, s[12:13]
	global_load_lds_dwordx4 v[214:215], off
	s_mov_b32 m0, s70
	v_lshl_add_u64 v[214:215], s[24:25], 0, v[132:133]
	global_load_lds_dwordx4 v[214:215], off
	s_mov_b32 m0, s66
	v_lshl_add_u64 v[214:215], s[24:25], 0, v[136:137]
	global_load_lds_dwordx4 v[214:215], off
	s_mov_b32 m0, s51
	v_lshl_add_u64 v[214:215], v[218:219], 0, s[12:13]
	global_load_lds_dwordx4 v[214:215], off
	s_mov_b32 m0, s52
	v_lshl_add_u64 v[214:215], v[220:221], 0, s[12:13]
	global_load_lds_dwordx4 v[214:215], off
	s_waitcnt vmcnt(8) lgkmcnt(0)
	s_setprio 1
	s_barrier
	v_mfma_f32_16x16x32_bf16 v[62:65], v[148:151], v[182:185], v[62:65]
	v_mfma_f32_16x16x32_bf16 v[58:61], v[158:161], v[182:185], v[58:61]
	v_mfma_f32_16x16x32_bf16 v[54:57], v[148:151], v[190:193], v[54:57]
	v_mfma_f32_16x16x32_bf16 v[46:49], v[158:161], v[190:193], v[46:49]
	v_mfma_f32_16x16x32_bf16 v[38:41], v[148:151], v[198:201], v[38:41]
	v_mfma_f32_16x16x32_bf16 v[30:33], v[158:161], v[198:201], v[30:33]
	v_mfma_f32_16x16x32_bf16 v[22:25], v[148:151], v[206:209], v[22:25]
	v_mfma_f32_16x16x32_bf16 v[14:17], v[158:161], v[206:209], v[14:17]
	v_mfma_f32_16x16x32_bf16 v[62:65], v[154:157], v[186:189], v[62:65]
	v_mfma_f32_16x16x32_bf16 v[58:61], v[162:165], v[186:189], v[58:61]
	v_mfma_f32_16x16x32_bf16 v[54:57], v[154:157], v[194:197], v[54:57]
	v_mfma_f32_16x16x32_bf16 v[46:49], v[162:165], v[194:197], v[46:49]
	v_mfma_f32_16x16x32_bf16 v[38:41], v[154:157], v[202:205], v[38:41]
	v_mfma_f32_16x16x32_bf16 v[30:33], v[162:165], v[202:205], v[30:33]
	v_mfma_f32_16x16x32_bf16 v[22:25], v[154:157], v[210:213], v[22:25]
	v_mfma_f32_16x16x32_bf16 v[14:17], v[162:165], v[210:213], v[14:17]
	s_setprio 0
	s_setprio 1
	v_mfma_f32_16x16x32_bf16 v[50:53], v[166:169], v[182:185], v[50:53]
	v_mfma_f32_16x16x32_bf16 v[42:45], v[174:177], v[182:185], v[42:45]
	v_mfma_f32_16x16x32_bf16 v[34:37], v[166:169], v[190:193], v[34:37]
	v_mfma_f32_16x16x32_bf16 v[26:29], v[174:177], v[190:193], v[26:29]
	v_mfma_f32_16x16x32_bf16 v[18:21], v[166:169], v[198:201], v[18:21]
	v_mfma_f32_16x16x32_bf16 v[10:13], v[174:177], v[198:201], v[10:13]
	v_mfma_f32_16x16x32_bf16 v[6:9], v[166:169], v[206:209], v[6:9]
	v_mfma_f32_16x16x32_bf16 v[2:5], v[174:177], v[206:209], v[2:5]
	v_mfma_f32_16x16x32_bf16 v[50:53], v[170:173], v[186:189], v[50:53]
	v_mfma_f32_16x16x32_bf16 v[42:45], v[178:181], v[186:189], v[42:45]
	v_mfma_f32_16x16x32_bf16 v[34:37], v[170:173], v[194:197], v[34:37]
	v_mfma_f32_16x16x32_bf16 v[26:29], v[178:181], v[194:197], v[26:29]
	v_mfma_f32_16x16x32_bf16 v[18:21], v[170:173], v[202:205], v[18:21]
	v_mfma_f32_16x16x32_bf16 v[10:13], v[178:181], v[202:205], v[10:13]
	v_mfma_f32_16x16x32_bf16 v[6:9], v[170:173], v[210:213], v[6:9]
	v_mfma_f32_16x16x32_bf16 v[2:5], v[178:181], v[210:213], v[2:5]
	s_setprio 0
	s_barrier
	s_movk_i32 s26, 0x100
	s_andn2_b64 vcc, exec, s[22:23]
	s_mov_b64 s[24:25], -1
	s_mov_b64 s[22:23], 0
	s_cbranch_vccz .LBB0_588
	s_and_b64 vcc, exec, s[14:15]
	s_cbranch_vccz .LBB0_591
	s_barrier

; #define PG8_STAGE(bufoff, gbase, voff) do { _Pragma("unroll") for (int _i = 0; _i < 2; ++_i) \
;         __builtin_amdgcn_global_load_lds((const unsigned*)((const char*)(gbase) + (voff)[_i]), (LAS unsigned*)(lds + (bufoff) + ldsw + _i * 8192), 16, 0, 0); } while (0)
; #define PG8_LDA(dst, b, h) do { _Pragma("unroll") for (int m = 0; m < 4; ++m) _Pragma("unroll") for (int k = 0; k < 2; ++k) dst[m][k] = *(const LAS bf16x8*)(lds + PG8_SA(b, h) + aoff + m * 2048 + k * 1024); } while (0)
; #define PG8_LDB(dst, b, h) do { _Pragma("unroll") for (int n = 0; n < 2; ++n) _Pragma("unroll") for (int k = 0; k < 2; ++k) dst[n][k] = *(const LAS bf16x8*)(lds + PG8_SB(b, h) + boff + n * 2048 + k * 1024); } while (0)
; #define PG8_MMA(ai, bj, At, Bt) do { __builtin_amdgcn_s_setprio(1); _Pragma("unroll") for (int m = 0; m < 4; ++m) _Pragma("unroll") for (int n = 0; n < 2; ++n) _Pragma("unroll") for (int k = 0; k < 2; ++k) \
;         acc[ai][bj][m][n] = __builtin_amdgcn_mfma_f32_16x16x32_bf16(Bt[n][k], At[m][k], acc[ai][bj][m][n], 0, 0, 0); __builtin_amdgcn_s_setprio(0); } while (0)
; #define PG8_BAR __builtin_amdgcn_s_barrier()
; template <class Epi, class Sched, bool ALIGN_EPI = false, bool SP2 = false>
; __device__ __forceinline__ void gemm_phase(LAS unsigned char* lds, const Gemm g, const Sched& S, const Epi& E) {
;     ...
;         const bool has_next = S.next(ui + 1, nxt);
;         const char* nA = has_next ? (const char*)g.A + (size_t)nxt.pm * tstepA : cA; const char* nB = has_next ? (const char*)g.Bt + (size_t)nxt.pn * tstepB : cB;
;         for (int t = 0; t < nt; t += 2) {
;             const bool last = (t == nt - 2);
;             const char* a1 = cA + (size_t)(t + 1) * kstep;
;             const char* a2 = last ? nA : cA + (size_t)(t + 2) * kstep; const char* b2 = last ? nB : cB + (size_t)(t + 2) * kstep;
;             const char* a3 = a2 + kstep; const char* b3 = b2 + kstep;
;             if (last && has_next) S.a_ready(nxt);
;             if constexpr (SP2) {
;             PG8_LDB(B0, 0, 0); PG8_LDB(B1, 0, 1); PG8_SCHED; PG8_LDA(At, 0, 0); PG8_STAGE(PG8_SA(1, 1), a1 + hstepA, voffA);
;             PG8_WAIT_V(8); PG8_WAIT_L(0); PG8_BAR; PG8_MMA(0, 0, At, B0); PG8_MMA(0, 1, At, B1); PG8_BAR; PG8_SCHED;
;             PG8_LDA(At, 0, 1); PG8_STAGE(PG8_SB(0, 0), b2, voffB); PG8_STAGE(PG8_SB(0, 1), b2 + hstepB, voffB); PG8_STAGE(PG8_SA(0, 0), a2, voffA);
.LBB0_968:
	ds_read_b128 v[120:123], v221
	ds_read_b128 v[124:127], v221 offset:1024
	ds_read_b128 v[136:139], v221 offset:2048
	ds_read_b128 v[140:143], v221 offset:3072
	ds_read_b128 v[144:147], v222
	ds_read_b128 v[148:151], v222 offset:1024
	ds_read_b128 v[170:173], v222 offset:2048
	ds_read_b128 v[174:177], v222 offset:3072
	s_add_u32 s28, s26, 0xfff80080
	s_addc_u32 s29, s27, -1
	s_cmp_eq_u32 s50, 28
	s_cselect_b32 s31, s17, s29
	s_cselect_b32 s30, s23, s28
	s_cselect_b32 s29, s15, s49
	s_cselect_b32 s28, s25, s33
	v_lshl_add_u64 v[210:211], s[26:27], 0, v[162:163]
	s_add_i32 m0, s35, 0xc000
	ds_read_b128 v[178:181], v223
	ds_read_b128 v[182:185], v223 offset:1024
	ds_read_b128 v[186:189], v223 offset:2048
	ds_read_b128 v[190:193], v223 offset:3072
	ds_read_b128 v[194:197], v223 offset:4096
	ds_read_b128 v[198:201], v223 offset:5120
	ds_read_b128 v[202:205], v223 offset:6144
	ds_read_b128 v[206:209], v223 offset:7168
	global_load_lds_dwordx4 v[210:211], off
	s_add_i32 m0, s35, 0xe000
	v_lshl_add_u64 v[210:211], s[26:27], 0, v[164:165]
	global_load_lds_dwordx4 v[210:211], off
	s_waitcnt vmcnt(8) lgkmcnt(0)
	s_setprio 1
	s_barrier
	v_mfma_f32_16x16x32_bf16 v[132:135], v[120:123], v[178:181], v[132:135]
	v_mfma_f32_16x16x32_bf16 v[128:131], v[136:139], v[178:181], v[128:131]
	v_mfma_f32_16x16x32_bf16 v[100:103], v[120:123], v[186:189], v[100:103]
	v_mfma_f32_16x16x32_bf16 v[96:99], v[136:139], v[186:189], v[96:99]
	v_mfma_f32_16x16x32_bf16 v[116:119], v[120:123], v[194:197], v[116:119]
	v_mfma_f32_16x16x32_bf16 v[112:115], v[136:139], v[194:197], v[112:115]
	v_mfma_f32_16x16x32_bf16 v[108:111], v[120:123], v[202:205], v[108:111]
	v_mfma_f32_16x16x32_bf16 v[104:107], v[136:139], v[202:205], v[104:107]
	v_mfma_f32_16x16x32_bf16 v[132:135], v[124:127], v[182:185], v[132:135]
	v_mfma_f32_16x16x32_bf16 v[128:131], v[140:143], v[182:185], v[128:131]
	v_mfma_f32_16x16x32_bf16 v[100:103], v[124:127], v[190:193], v[100:103]
	v_mfma_f32_16x16x32_bf16 v[96:99], v[140:143], v[190:193], v[96:99]
	v_mfma_f32_16x16x32_bf16 v[116:119], v[124:127], v[198:201], v[116:119]
	v_mfma_f32_16x16x32_bf16 v[112:115], v[140:143], v[198:201], v[112:115]
	v_mfma_f32_16x16x32_bf16 v[108:111], v[124:127], v[206:209], v[108:111]
	v_mfma_f32_16x16x32_bf16 v[104:107], v[140:143], v[206:209], v[104:107]
	s_setprio 0
	s_setprio 1
	v_mfma_f32_16x16x32_bf16 v[60:63], v[144:147], v[178:181], v[60:63]
	v_mfma_f32_16x16x32_bf16 v[56:59], v[170:173], v[178:181], v[56:59]
	v_mfma_f32_16x16x32_bf16 v[52:55], v[144:147], v[186:189], v[52:55]
	v_mfma_f32_16x16x32_bf16 v[48:51], v[170:173], v[186:189], v[48:51]
	v_mfma_f32_16x16x32_bf16 v[44:47], v[144:147], v[194:197], v[44:47]
	v_mfma_f32_16x16x32_bf16 v[40:43], v[170:173], v[194:197], v[40:43]
	v_mfma_f32_16x16x32_bf16 v[36:39], v[144:147], v[202:205], v[36:39]
	v_mfma_f32_16x16x32_bf16 v[32:35], v[170:173], v[202:205], v[32:35]
	v_mfma_f32_16x16x32_bf16 v[60:63], v[148:151], v[182:185], v[60:63]
	v_mfma_f32_16x16x32_bf16 v[56:59], v[174:177], v[182:185], v[56:59]
	v_mfma_f32_16x16x32_bf16 v[52:55], v[148:151], v[190:193], v[52:55]
	v_mfma_f32_16x16x32_bf16 v[48:51], v[174:177], v[190:193], v[48:51]
	v_mfma_f32_16x16x32_bf16 v[44:47], v[148:151], v[198:201], v[44:47]
	v_mfma_f32_16x16x32_bf16 v[40:43], v[174:177], v[198:201], v[40:43]
	v_mfma_f32_16x16x32_bf16 v[36:39], v[148:151], v[206:209], v[36:39]
	v_mfma_f32_16x16x32_bf16 v[32:35], v[174:177], v[206:209], v[32:35]
	s_setprio 0
	s_barrier
	s_add_i32 s51, s45, s34
	v_lshl_add_u64 v[210:211], s[28:29], 0, v[156:157]
	s_mov_b32 m0, s51
	ds_read_b128 v[178:181], v223 offset:16384
	ds_read_b128 v[182:185], v223 offset:17408
	ds_read_b128 v[186:189], v223 offset:18432
	ds_read_b128 v[190:193], v223 offset:19456
	ds_read_b128 v[194:197], v223 offset:20480
	ds_read_b128 v[198:201], v223 offset:21504
	ds_read_b128 v[202:205], v223 offset:22528
	ds_read_b128 v[206:209], v223 offset:23552
	global_load_lds_dwordx4 v[210:211], off
	s_add_i32 m0, s51, 0x2000
	s_add_u32 s52, s28, 0x80000
	v_lshl_add_u64 v[212:213], s[28:29], 0, v[160:161]
	s_addc_u32 s53, s29, 0
	s_add_i32 s51, s46, s34
	global_load_lds_dwordx4 v[212:213], off
	v_lshl_add_u64 v[214:215], s[52:53], 0, v[156:157]
	s_mov_b32 m0, s51
	v_lshl_add_u64 v[216:217], s[30:31], 0, v[158:159]
	global_load_lds_dwordx4 v[214:215], off
	s_add_i32 m0, s51, 0x2000
	v_lshl_add_u64 v[214:215], s[52:53], 0, v[160:161]
	global_load_lds_dwordx4 v[214:215], off
	s_mov_b32 m0, s35
	v_lshl_add_u64 v[214:215], s[30:31], 0, v[154:155]
	global_load_lds_dwordx4 v[214:215], off
	s_mov_b32 m0, s36
	s_nop 0
	global_load_lds_dwordx4 v[216:217], off
	s_waitcnt vmcnt(8) lgkmcnt(0)
	s_setprio 1
	s_barrier
; #define PG8_STAGE(bufoff, gbase, voff) do { _Pragma("unroll") for (int _i = 0; _i < 2; ++_i) \
;         __builtin_amdgcn_global_load_lds((const unsigned*)((const char*)(gbase) + (voff)[_i]), (LAS unsigned*)(lds + (bufoff) + ldsw + _i * 8192), 16, 0, 0); } while (0)
; #define PG8_LDA(dst, b, h) do { _Pragma("unroll") for (int m = 0; m < 4; ++m) _Pragma("unroll") for (int k = 0; k < 2; ++k) dst[m][k] = *(const LAS bf16x8*)(lds + PG8_SA(b, h) + aoff + m * 2048 + k * 1024); } while (0)
; #define PG8_LDB(dst, b, h) do { _Pragma("unroll") for (int n = 0; n < 2; ++n) _Pragma("unroll") for (int k = 0; k < 2; ++k) dst[n][k] = *(const LAS bf16x8*)(lds + PG8_SB(b, h) + boff + n * 2048 + k * 1024); } while (0)
; #define PG8_MMA(ai, bj, At, Bt) do { __builtin_amdgcn_s_setprio(1); _Pragma("unroll") for (int m = 0; m < 4; ++m) _Pragma("unroll") for (int n = 0; n < 2; ++n) _Pragma("unroll") for (int k = 0; k < 2; ++k) \
;         acc[ai][bj][m][n] = __builtin_amdgcn_mfma_f32_16x16x32_bf16(Bt[n][k], At[m][k], acc[ai][bj][m][n], 0, 0, 0); __builtin_amdgcn_s_setprio(0); } while (0)
; #define PG8_WAIT_V(n) asm volatile("s_waitcnt vmcnt(" #n ")" ::: "memory")
; #define PG8_WAIT_L(n) asm volatile("s_waitcnt lgkmcnt(" #n ")" ::: "memory")
; #define PG8_BAR __builtin_amdgcn_s_barrier()
; #define PG8_SCHED __builtin_amdgcn_sched_barrier(0)
; template <class Epi, class Sched, bool ALIGN_EPI = false, bool SP2 = false>
; __device__ __forceinline__ void gemm_phase(LAS unsigned char* lds, const Gemm g, const Sched& S, const Epi& E) {
;     ...
;             PG8_WAIT_V(8); PG8_WAIT_L(0); PG8_BAR; PG8_MMA(1, 0, At, B0); PG8_MMA(1, 1, At, B1); PG8_BAR; PG8_SCHED;
;             PG8_LDB(B0, 1, 0); PG8_LDB(B1, 1, 1); PG8_SCHED; PG8_LDA(At, 1, 0); PG8_STAGE(PG8_SA(0, 1), a2 + hstepA, voffA);
;             PG8_WAIT_V(8); PG8_WAIT_L(0); PG8_BAR; PG8_MMA(0, 0, At, B0); PG8_MMA(0, 1, At, B1); PG8_BAR; PG8_SCHED;
	v_mfma_f32_16x16x32_bf16 v[92:95], v[120:123], v[178:181], v[92:95]
	v_mfma_f32_16x16x32_bf16 v[88:91], v[136:139], v[178:181], v[88:91]
	v_mfma_f32_16x16x32_bf16 v[84:87], v[120:123], v[186:189], v[84:87]
	v_mfma_f32_16x16x32_bf16 v[80:83], v[136:139], v[186:189], v[80:83]
	v_mfma_f32_16x16x32_bf16 v[76:79], v[120:123], v[194:197], v[76:79]
	v_mfma_f32_16x16x32_bf16 v[72:75], v[136:139], v[194:197], v[72:75]
	v_mfma_f32_16x16x32_bf16 v[68:71], v[120:123], v[202:205], v[68:71]
	v_mfma_f32_16x16x32_bf16 v[64:67], v[136:139], v[202:205], v[64:67]
	v_mfma_f32_16x16x32_bf16 v[92:95], v[124:127], v[182:185], v[92:95]
	v_mfma_f32_16x16x32_bf16 v[88:91], v[140:143], v[182:185], v[88:91]
	v_mfma_f32_16x16x32_bf16 v[84:87], v[124:127], v[190:193], v[84:87]
	v_mfma_f32_16x16x32_bf16 v[80:83], v[140:143], v[190:193], v[80:83]
	v_mfma_f32_16x16x32_bf16 v[76:79], v[124:127], v[198:201], v[76:79]
	v_mfma_f32_16x16x32_bf16 v[72:75], v[140:143], v[198:201], v[72:75]
	v_mfma_f32_16x16x32_bf16 v[68:71], v[124:127], v[206:209], v[68:71]
	v_mfma_f32_16x16x32_bf16 v[64:67], v[140:143], v[206:209], v[64:67]
	s_setprio 0
	s_setprio 1
	v_mfma_f32_16x16x32_bf16 v[28:31], v[144:147], v[178:181], v[28:31]
	v_mfma_f32_16x16x32_bf16 v[24:27], v[170:173], v[178:181], v[24:27]
	v_mfma_f32_16x16x32_bf16 v[20:23], v[144:147], v[186:189], v[20:23]
	v_mfma_f32_16x16x32_bf16 v[16:19], v[170:173], v[186:189], v[16:19]
	v_mfma_f32_16x16x32_bf16 v[12:15], v[144:147], v[194:197], v[12:15]
	v_mfma_f32_16x16x32_bf16 v[8:11], v[170:173], v[194:197], v[8:11]
	v_mfma_f32_16x16x32_bf16 v[4:7], v[144:147], v[202:205], v[4:7]
	v_mfma_f32_16x16x32_bf16 v[0:3], v[170:173], v[202:205], v[0:3]
	v_mfma_f32_16x16x32_bf16 v[28:31], v[148:151], v[182:185], v[28:31]
	v_mfma_f32_16x16x32_bf16 v[24:27], v[174:177], v[182:185], v[24:27]
	v_mfma_f32_16x16x32_bf16 v[20:23], v[148:151], v[190:193], v[20:23]
	v_mfma_f32_16x16x32_bf16 v[16:19], v[174:177], v[190:193], v[16:19]
	v_mfma_f32_16x16x32_bf16 v[12:15], v[148:151], v[198:201], v[12:15]
	v_mfma_f32_16x16x32_bf16 v[8:11], v[174:177], v[198:201], v[8:11]
	v_mfma_f32_16x16x32_bf16 v[4:7], v[148:151], v[206:209], v[4:7]
	v_mfma_f32_16x16x32_bf16 v[0:3], v[174:177], v[206:209], v[0:3]
	s_setprio 0
	s_barrier
	ds_read_b128 v[120:123], v225
	ds_read_b128 v[124:127], v225 offset:1024
	ds_read_b128 v[136:139], v225 offset:2048
	ds_read_b128 v[140:143], v225 offset:3072
	ds_read_b128 v[144:147], v226
	ds_read_b128 v[148:151], v226 offset:1024
	ds_read_b128 v[170:173], v226 offset:2048
	ds_read_b128 v[174:177], v226 offset:3072
	s_add_u32 s30, s30, 0x80000
	s_addc_u32 s31, s31, 0
	s_mov_b32 m0, s37
	v_lshl_add_u64 v[218:219], s[30:31], 0, v[154:155]
	ds_read_b128 v[178:181], v223 offset:32768
	ds_read_b128 v[182:185], v223 offset:33792
	ds_read_b128 v[186:189], v223 offset:34816
	ds_read_b128 v[190:193], v223 offset:35840
	ds_read_b128 v[194:197], v223 offset:36864
	ds_read_b128 v[198:201], v223 offset:37888
	ds_read_b128 v[202:205], v223 offset:38912
	ds_read_b128 v[206:209], v223 offset:39936
	global_load_lds_dwordx4 v[218:219], off
	s_mov_b32 m0, s38
	v_lshl_add_u64 v[218:219], s[30:31], 0, v[158:159]
	global_load_lds_dwordx4 v[218:219], off
	s_waitcnt vmcnt(8) lgkmcnt(0)
	s_setprio 1
	s_barrier
	v_mfma_f32_16x16x32_bf16 v[132:135], v[120:123], v[178:181], v[132:135]
	v_mfma_f32_16x16x32_bf16 v[128:131], v[136:139], v[178:181], v[128:131]
	v_mfma_f32_16x16x32_bf16 v[100:103], v[120:123], v[186:189], v[100:103]
	v_mfma_f32_16x16x32_bf16 v[96:99], v[136:139], v[186:189], v[96:99]
	v_mfma_f32_16x16x32_bf16 v[116:119], v[120:123], v[194:197], v[116:119]
	v_mfma_f32_16x16x32_bf16 v[112:115], v[136:139], v[194:197], v[112:115]
	v_mfma_f32_16x16x32_bf16 v[108:111], v[120:123], v[202:205], v[108:111]
	v_mfma_f32_16x16x32_bf16 v[104:107], v[136:139], v[202:205], v[104:107]
	v_mfma_f32_16x16x32_bf16 v[132:135], v[124:127], v[182:185], v[132:135]
	v_mfma_f32_16x16x32_bf16 v[128:131], v[140:143], v[182:185], v[128:131]
	v_mfma_f32_16x16x32_bf16 v[100:103], v[124:127], v[190:193], v[100:103]
	v_mfma_f32_16x16x32_bf16 v[96:99], v[140:143], v[190:193], v[96:99]
	v_mfma_f32_16x16x32_bf16 v[116:119], v[124:127], v[198:201], v[116:119]
	v_mfma_f32_16x16x32_bf16 v[112:115], v[140:143], v[198:201], v[112:115]
	v_mfma_f32_16x16x32_bf16 v[108:111], v[124:127], v[206:209], v[108:111]
	v_mfma_f32_16x16x32_bf16 v[104:107], v[140:143], v[206:209], v[104:107]
	s_setprio 0
	s_setprio 1
	v_mfma_f32_16x16x32_bf16 v[60:63], v[144:147], v[178:181], v[60:63]
	v_mfma_f32_16x16x32_bf16 v[56:59], v[170:173], v[178:181], v[56:59]
	v_mfma_f32_16x16x32_bf16 v[52:55], v[144:147], v[186:189], v[52:55]
	v_mfma_f32_16x16x32_bf16 v[48:51], v[170:173], v[186:189], v[48:51]
	v_mfma_f32_16x16x32_bf16 v[44:47], v[144:147], v[194:197], v[44:47]
	v_mfma_f32_16x16x32_bf16 v[40:43], v[170:173], v[194:197], v[40:43]
	v_mfma_f32_16x16x32_bf16 v[36:39], v[144:147], v[202:205], v[36:39]
	v_mfma_f32_16x16x32_bf16 v[32:35], v[170:173], v[202:205], v[32:35]
	v_mfma_f32_16x16x32_bf16 v[60:63], v[148:151], v[182:185], v[60:63]
	v_mfma_f32_16x16x32_bf16 v[56:59], v[174:177], v[182:185], v[56:59]
	v_mfma_f32_16x16x32_bf16 v[52:55], v[148:151], v[190:193], v[52:55]
	v_mfma_f32_16x16x32_bf16 v[48:51], v[174:177], v[190:193], v[48:51]
	v_mfma_f32_16x16x32_bf16 v[44:47], v[148:151], v[198:201], v[44:47]
	v_mfma_f32_16x16x32_bf16 v[40:43], v[174:177], v[198:201], v[40:43]
	v_mfma_f32_16x16x32_bf16 v[36:39], v[148:151], v[206:209], v[36:39]
	v_mfma_f32_16x16x32_bf16 v[32:35], v[174:177], v[206:209], v[32:35]
	s_setprio 0
	s_barrier
; #define PG8_STAGE(bufoff, gbase, voff) do { _Pragma("unroll") for (int _i = 0; _i < 2; ++_i) \
;         __builtin_amdgcn_global_load_lds((const unsigned*)((const char*)(gbase) + (voff)[_i]), (LAS unsigned*)(lds + (bufoff) + ldsw + _i * 8192), 16, 0, 0); } while (0)
; #define PG8_LDA(dst, b, h) do { _Pragma("unroll") for (int m = 0; m < 4; ++m) _Pragma("unroll") for (int k = 0; k < 2; ++k) dst[m][k] = *(const LAS bf16x8*)(lds + PG8_SA(b, h) + aoff + m * 2048 + k * 1024); } while (0)
; #define PG8_MMA(ai, bj, At, Bt) do { __builtin_amdgcn_s_setprio(1); _Pragma("unroll") for (int m = 0; m < 4; ++m) _Pragma("unroll") for (int n = 0; n < 2; ++n) _Pragma("unroll") for (int k = 0; k < 2; ++k) \
;         acc[ai][bj][m][n] = __builtin_amdgcn_mfma_f32_16x16x32_bf16(Bt[n][k], At[m][k], acc[ai][bj][m][n], 0, 0, 0); __builtin_amdgcn_s_setprio(0); } while (0)
; #define PG8_WAIT_V(n) asm volatile("s_waitcnt vmcnt(" #n ")" ::: "memory")
; #define PG8_WAIT_L(n) asm volatile("s_waitcnt lgkmcnt(" #n ")" ::: "memory")
; #define PG8_BAR __builtin_amdgcn_s_barrier()
; #define PG8_SCHED __builtin_amdgcn_sched_barrier(0)
; template <class Epi, class Sched, bool ALIGN_EPI = false, bool SP2 = false>
; __device__ __forceinline__ void gemm_phase(LAS unsigned char* lds, const Gemm g, const Sched& S, const Epi& E) {
;     ...
;             PG8_LDA(At, 1, 1); PG8_STAGE(PG8_SB(1, 0), b3, voffB); PG8_STAGE(PG8_SB(1, 1), b3 + hstepB, voffB); PG8_STAGE(PG8_SA(1, 0), a3, voffA);
;             PG8_WAIT_V(8); PG8_WAIT_L(0); PG8_BAR; PG8_MMA(1, 0, At, B0); PG8_MMA(1, 1, At, B1); PG8_BAR; PG8_SCHED;
;     ...
;         if constexpr (ALIGN_EPI) { if (wr == 0) PG8_BAR; }
	s_add_i32 s30, s47, s34
	v_lshl_add_u64 v[210:211], v[210:211], 0, s[10:11]
	s_mov_b32 m0, s30
	ds_read_b128 v[178:181], v223 offset:49152
	ds_read_b128 v[182:185], v223 offset:50176
	ds_read_b128 v[186:189], v223 offset:51200
	ds_read_b128 v[190:193], v223 offset:52224
	ds_read_b128 v[194:197], v223 offset:53248
	ds_read_b128 v[198:201], v223 offset:54272
	ds_read_b128 v[202:205], v223 offset:55296
	ds_read_b128 v[206:209], v223 offset:56320
	global_load_lds_dwordx4 v[210:211], off
	s_add_i32 m0, s30, 0x2000
	s_add_u32 s28, s28, 0x80080
	v_lshl_add_u64 v[210:211], v[212:213], 0, s[10:11]
	s_addc_u32 s29, s29, 0
	s_add_i32 s30, s48, s34
	global_load_lds_dwordx4 v[210:211], off
	s_mov_b32 m0, s30
	v_lshl_add_u64 v[210:211], s[28:29], 0, v[156:157]
	global_load_lds_dwordx4 v[210:211], off
	s_add_i32 m0, s30, 0x2000
	v_lshl_add_u64 v[210:211], s[28:29], 0, v[160:161]
	global_load_lds_dwordx4 v[210:211], off
	s_mov_b32 m0, s39
	v_lshl_add_u64 v[210:211], v[214:215], 0, s[10:11]
	global_load_lds_dwordx4 v[210:211], off
	s_mov_b32 m0, s40
	v_lshl_add_u64 v[210:211], v[216:217], 0, s[10:11]
	global_load_lds_dwordx4 v[210:211], off
	s_waitcnt vmcnt(8) lgkmcnt(0)
	s_setprio 1
	s_barrier
	v_mfma_f32_16x16x32_bf16 v[92:95], v[120:123], v[178:181], v[92:95]
	v_mfma_f32_16x16x32_bf16 v[88:91], v[136:139], v[178:181], v[88:91]
	v_mfma_f32_16x16x32_bf16 v[84:87], v[120:123], v[186:189], v[84:87]
	v_mfma_f32_16x16x32_bf16 v[80:83], v[136:139], v[186:189], v[80:83]
	v_mfma_f32_16x16x32_bf16 v[76:79], v[120:123], v[194:197], v[76:79]
	v_mfma_f32_16x16x32_bf16 v[72:75], v[136:139], v[194:197], v[72:75]
	v_mfma_f32_16x16x32_bf16 v[68:71], v[120:123], v[202:205], v[68:71]
	v_mfma_f32_16x16x32_bf16 v[64:67], v[136:139], v[202:205], v[64:67]
	v_mfma_f32_16x16x32_bf16 v[92:95], v[124:127], v[182:185], v[92:95]
	v_mfma_f32_16x16x32_bf16 v[88:91], v[140:143], v[182:185], v[88:91]
	v_mfma_f32_16x16x32_bf16 v[84:87], v[124:127], v[190:193], v[84:87]
	v_mfma_f32_16x16x32_bf16 v[80:83], v[140:143], v[190:193], v[80:83]
	v_mfma_f32_16x16x32_bf16 v[76:79], v[124:127], v[198:201], v[76:79]
	v_mfma_f32_16x16x32_bf16 v[72:75], v[140:143], v[198:201], v[72:75]
	v_mfma_f32_16x16x32_bf16 v[68:71], v[124:127], v[206:209], v[68:71]
	v_mfma_f32_16x16x32_bf16 v[64:67], v[140:143], v[206:209], v[64:67]
	s_setprio 0
	s_setprio 1
	v_mfma_f32_16x16x32_bf16 v[28:31], v[144:147], v[178:181], v[28:31]
	v_mfma_f32_16x16x32_bf16 v[24:27], v[170:173], v[178:181], v[24:27]
	v_mfma_f32_16x16x32_bf16 v[20:23], v[144:147], v[186:189], v[20:23]
	v_mfma_f32_16x16x32_bf16 v[16:19], v[170:173], v[186:189], v[16:19]
	v_mfma_f32_16x16x32_bf16 v[12:15], v[144:147], v[194:197], v[12:15]
	v_mfma_f32_16x16x32_bf16 v[8:11], v[170:173], v[194:197], v[8:11]
	v_mfma_f32_16x16x32_bf16 v[4:7], v[144:147], v[202:205], v[4:7]
	v_mfma_f32_16x16x32_bf16 v[0:3], v[170:173], v[202:205], v[0:3]
	v_mfma_f32_16x16x32_bf16 v[28:31], v[148:151], v[182:185], v[28:31]
	v_mfma_f32_16x16x32_bf16 v[24:27], v[174:177], v[182:185], v[24:27]
	v_mfma_f32_16x16x32_bf16 v[20:23], v[148:151], v[190:193], v[20:23]
	v_mfma_f32_16x16x32_bf16 v[16:19], v[174:177], v[190:193], v[16:19]
	v_mfma_f32_16x16x32_bf16 v[12:15], v[148:151], v[198:201], v[12:15]
	v_mfma_f32_16x16x32_bf16 v[8:11], v[174:177], v[198:201], v[8:11]
	v_mfma_f32_16x16x32_bf16 v[4:7], v[148:151], v[206:209], v[4:7]
	v_mfma_f32_16x16x32_bf16 v[0:3], v[174:177], v[206:209], v[0:3]
	s_add_i32 s50, s50, 2
	s_add_u32 s26, s26, 0x100
	s_addc_u32 s27, s27, 0
	s_add_u32 s33, s33, 0x100
	s_addc_u32 s49, s49, 0
	s_setprio 0
	s_barrier
	s_cmp_gt_u32 s50, 29
	s_cbranch_scc0 .LBB0_968
	s_and_b64 vcc, exec, s[12:13]
	s_cbranch_vccz .LBB0_971
	s_barrier

; #define PG8_STAGE(bufoff, gbase, voff) do { _Pragma("unroll") for (int _i = 0; _i < 2; ++_i) \
;         __builtin_amdgcn_global_load_lds((const unsigned*)((const char*)(gbase) + (voff)[_i]), (LAS unsigned*)(lds + (bufoff) + ldsw + _i * 8192), 16, 0, 0); } while (0)
; #define PG8_LDA(dst, b, h) do { _Pragma("unroll") for (int m = 0; m < 4; ++m) _Pragma("unroll") for (int k = 0; k < 2; ++k) dst[m][k] = *(const LAS bf16x8*)(lds + PG8_SA(b, h) + aoff + m * 2048 + k * 1024); } while (0)
; #define PG8_LDB(dst, b, h) do { _Pragma("unroll") for (int n = 0; n < 2; ++n) _Pragma("unroll") for (int k = 0; k < 2; ++k) dst[n][k] = *(const LAS bf16x8*)(lds + PG8_SB(b, h) + boff + n * 2048 + k * 1024); } while (0)
; #define PG8_MMA(ai, bj, At, Bt) do { __builtin_amdgcn_s_setprio(1); _Pragma("unroll") for (int m = 0; m < 4; ++m) _Pragma("unroll") for (int n = 0; n < 2; ++n) _Pragma("unroll") for (int k = 0; k < 2; ++k) \
;         acc[ai][bj][m][n] = __builtin_amdgcn_mfma_f32_16x16x32_bf16(Bt[n][k], At[m][k], acc[ai][bj][m][n], 0, 0, 0); __builtin_amdgcn_s_setprio(0); } while (0)
; #define PG8_BAR __builtin_amdgcn_s_barrier()
; template <class Epi, class Sched, bool ALIGN_EPI = false, bool SP2 = false>
; __device__ __forceinline__ void gemm_phase(LAS unsigned char* lds, const Gemm g, const Sched& S, const Epi& E) {
;     ...
;         const bool has_next = S.next(ui + 1, nxt);
;         const char* nA = has_next ? (const char*)g.A + (size_t)nxt.pm * tstepA : cA; const char* nB = has_next ? (const char*)g.Bt + (size_t)nxt.pn * tstepB : cB;
;         for (int t = 0; t < nt; t += 2) {
;             const bool last = (t == nt - 2);
;             const char* a1 = cA + (size_t)(t + 1) * kstep;
;             const char* a2 = last ? nA : cA + (size_t)(t + 2) * kstep; const char* b2 = last ? nB : cB + (size_t)(t + 2) * kstep;
;             const char* a3 = a2 + kstep; const char* b3 = b2 + kstep;
;             if (last && has_next) S.a_ready(nxt);
;             if constexpr (SP2) {
;             PG8_LDB(B0, 0, 0); PG8_LDB(B1, 0, 1); PG8_SCHED; PG8_LDA(At, 0, 0); PG8_STAGE(PG8_SA(1, 1), a1 + hstepA, voffA);
;             PG8_WAIT_V(8); PG8_WAIT_L(0); PG8_BAR; PG8_MMA(0, 0, At, B0); PG8_MMA(0, 1, At, B1); PG8_BAR; PG8_SCHED;
;             PG8_LDA(At, 0, 1); PG8_STAGE(PG8_SB(0, 0), b2, voffB); PG8_STAGE(PG8_SB(0, 1), b2 + hstepB, voffB); PG8_STAGE(PG8_SA(0, 0), a2, voffA);
.LBB0_1055:
	ds_read_b128 v[80:83], v171
	ds_read_b128 v[88:91], v171 offset:1024
	ds_read_b128 v[92:95], v171 offset:2048
	ds_read_b128 v[96:99], v171 offset:3072
	ds_read_b128 v[162:165], v172
	ds_read_b128 v[166:169], v172 offset:1024
	ds_read_b128 v[178:181], v172 offset:2048
	ds_read_b128 v[182:185], v172 offset:3072
	s_add_u32 s26, s24, 0xfff80080
	s_addc_u32 s27, s25, -1
	s_cmp_eq_u32 s53, 28
	s_cselect_b32 s29, s17, s27
	s_cselect_b32 s28, s49, s26
	s_cselect_b32 s27, s15, s52
	s_cselect_b32 s26, s50, s51
	v_lshl_add_u64 v[218:219], s[24:25], 0, v[154:155]
	s_add_i32 m0, s23, 0xc000
	ds_read_b128 v[186:189], v173
	ds_read_b128 v[190:193], v173 offset:1024
	ds_read_b128 v[194:197], v173 offset:2048
	ds_read_b128 v[198:201], v173 offset:3072
	ds_read_b128 v[202:205], v173 offset:4096
	ds_read_b128 v[206:209], v173 offset:5120
	ds_read_b128 v[210:213], v173 offset:6144
	ds_read_b128 v[214:217], v173 offset:7168
	global_load_lds_dwordx4 v[218:219], off
	s_add_i32 m0, s23, 0xe000
	v_lshl_add_u64 v[218:219], s[24:25], 0, v[156:157]
	global_load_lds_dwordx4 v[218:219], off
	s_waitcnt vmcnt(8) lgkmcnt(0)
	s_setprio 1
	s_barrier
	v_mfma_f32_16x16x32_bf16 v[140:143], v[80:83], v[186:189], v[140:143]
	v_mfma_f32_16x16x32_bf16 v[136:139], v[92:95], v[186:189], v[136:139]
	v_mfma_f32_16x16x32_bf16 v[124:127], v[80:83], v[194:197], v[124:127]
	v_mfma_f32_16x16x32_bf16 v[120:123], v[92:95], v[194:197], v[120:123]
	v_mfma_f32_16x16x32_bf16 v[108:111], v[80:83], v[202:205], v[108:111]
	v_mfma_f32_16x16x32_bf16 v[104:107], v[92:95], v[202:205], v[104:107]
	v_mfma_f32_16x16x32_bf16 v[76:79], v[80:83], v[210:213], v[76:79]
	v_mfma_f32_16x16x32_bf16 v[72:75], v[92:95], v[210:213], v[72:75]
	v_mfma_f32_16x16x32_bf16 v[140:143], v[88:91], v[190:193], v[140:143]
	v_mfma_f32_16x16x32_bf16 v[136:139], v[96:99], v[190:193], v[136:139]
	v_mfma_f32_16x16x32_bf16 v[124:127], v[88:91], v[198:201], v[124:127]
	v_mfma_f32_16x16x32_bf16 v[120:123], v[96:99], v[198:201], v[120:123]
	v_mfma_f32_16x16x32_bf16 v[108:111], v[88:91], v[206:209], v[108:111]
	v_mfma_f32_16x16x32_bf16 v[104:107], v[96:99], v[206:209], v[104:107]
	v_mfma_f32_16x16x32_bf16 v[76:79], v[88:91], v[214:217], v[76:79]
	v_mfma_f32_16x16x32_bf16 v[72:75], v[96:99], v[214:217], v[72:75]
	s_setprio 0
	s_setprio 1
	v_mfma_f32_16x16x32_bf16 v[132:135], v[162:165], v[186:189], v[132:135]
	v_mfma_f32_16x16x32_bf16 v[128:131], v[178:181], v[186:189], v[128:131]
	v_mfma_f32_16x16x32_bf16 v[116:119], v[162:165], v[194:197], v[116:119]
	v_mfma_f32_16x16x32_bf16 v[112:115], v[178:181], v[194:197], v[112:115]
	v_mfma_f32_16x16x32_bf16 v[100:103], v[162:165], v[202:205], v[100:103]
	v_mfma_f32_16x16x32_bf16 v[84:87], v[178:181], v[202:205], v[84:87]
	v_mfma_f32_16x16x32_bf16 v[68:71], v[162:165], v[210:213], v[68:71]
	v_mfma_f32_16x16x32_bf16 v[64:67], v[178:181], v[210:213], v[64:67]
	v_mfma_f32_16x16x32_bf16 v[132:135], v[166:169], v[190:193], v[132:135]
	v_mfma_f32_16x16x32_bf16 v[128:131], v[182:185], v[190:193], v[128:131]
	v_mfma_f32_16x16x32_bf16 v[116:119], v[166:169], v[198:201], v[116:119]
	v_mfma_f32_16x16x32_bf16 v[112:115], v[182:185], v[198:201], v[112:115]
	v_mfma_f32_16x16x32_bf16 v[100:103], v[166:169], v[206:209], v[100:103]
	v_mfma_f32_16x16x32_bf16 v[84:87], v[182:185], v[206:209], v[84:87]
	v_mfma_f32_16x16x32_bf16 v[68:71], v[166:169], v[214:217], v[68:71]
	v_mfma_f32_16x16x32_bf16 v[64:67], v[182:185], v[214:217], v[64:67]
	s_setprio 0
	s_barrier
	s_add_i32 s54, s43, s30
	v_lshl_add_u64 v[218:219], s[26:27], 0, v[146:147]
	s_mov_b32 m0, s54
	ds_read_b128 v[186:189], v173 offset:16384
	ds_read_b128 v[190:193], v173 offset:17408
	ds_read_b128 v[194:197], v173 offset:18432
	ds_read_b128 v[198:201], v173 offset:19456
	ds_read_b128 v[202:205], v173 offset:20480
	ds_read_b128 v[206:209], v173 offset:21504
	ds_read_b128 v[210:213], v173 offset:22528
	ds_read_b128 v[214:217], v173 offset:23552
	global_load_lds_dwordx4 v[218:219], off
	s_add_i32 m0, s54, 0x2000
	s_add_u32 s54, s26, 0x80000
	v_lshl_add_u64 v[220:221], s[26:27], 0, v[150:151]
	s_addc_u32 s55, s27, 0
	s_add_i32 s56, s44, s30
	global_load_lds_dwordx4 v[220:221], off
	v_lshl_add_u64 v[222:223], s[54:55], 0, v[146:147]
	s_mov_b32 m0, s56
	v_lshl_add_u64 v[224:225], s[28:29], 0, v[148:149]
	global_load_lds_dwordx4 v[222:223], off
	s_add_i32 m0, s56, 0x2000
	v_lshl_add_u64 v[222:223], s[54:55], 0, v[150:151]
	global_load_lds_dwordx4 v[222:223], off
	s_mov_b32 m0, s23
	v_lshl_add_u64 v[222:223], s[28:29], 0, v[144:145]
	global_load_lds_dwordx4 v[222:223], off
	s_mov_b32 m0, s35
	s_nop 0
	global_load_lds_dwordx4 v[224:225], off
	s_waitcnt vmcnt(8) lgkmcnt(0)
	s_setprio 1
	s_barrier
; #define PG8_STAGE(bufoff, gbase, voff) do { _Pragma("unroll") for (int _i = 0; _i < 2; ++_i) \
;         __builtin_amdgcn_global_load_lds((const unsigned*)((const char*)(gbase) + (voff)[_i]), (LAS unsigned*)(lds + (bufoff) + ldsw + _i * 8192), 16, 0, 0); } while (0)
; #define PG8_LDA(dst, b, h) do { _Pragma("unroll") for (int m = 0; m < 4; ++m) _Pragma("unroll") for (int k = 0; k < 2; ++k) dst[m][k] = *(const LAS bf16x8*)(lds + PG8_SA(b, h) + aoff + m * 2048 + k * 1024); } while (0)
; #define PG8_LDB(dst, b, h) do { _Pragma("unroll") for (int n = 0; n < 2; ++n) _Pragma("unroll") for (int k = 0; k < 2; ++k) dst[n][k] = *(const LAS bf16x8*)(lds + PG8_SB(b, h) + boff + n * 2048 + k * 1024); } while (0)
; #define PG8_MMA(ai, bj, At, Bt) do { __builtin_amdgcn_s_setprio(1); _Pragma("unroll") for (int m = 0; m < 4; ++m) _Pragma("unroll") for (int n = 0; n < 2; ++n) _Pragma("unroll") for (int k = 0; k < 2; ++k) \
;         acc[ai][bj][m][n] = __builtin_amdgcn_mfma_f32_16x16x32_bf16(Bt[n][k], At[m][k], acc[ai][bj][m][n], 0, 0, 0); __builtin_amdgcn_s_setprio(0); } while (0)
; #define PG8_WAIT_V(n) asm volatile("s_waitcnt vmcnt(" #n ")" ::: "memory")
; #define PG8_WAIT_L(n) asm volatile("s_waitcnt lgkmcnt(" #n ")" ::: "memory")
; #define PG8_BAR __builtin_amdgcn_s_barrier()
; #define PG8_SCHED __builtin_amdgcn_sched_barrier(0)
; template <class Epi, class Sched, bool ALIGN_EPI = false, bool SP2 = false>
; __device__ __forceinline__ void gemm_phase(LAS unsigned char* lds, const Gemm g, const Sched& S, const Epi& E) {
;     ...
;             PG8_WAIT_V(8); PG8_WAIT_L(0); PG8_BAR; PG8_MMA(1, 0, At, B0); PG8_MMA(1, 1, At, B1); PG8_BAR; PG8_SCHED;
;             PG8_LDB(B0, 1, 0); PG8_LDB(B1, 1, 1); PG8_SCHED; PG8_LDA(At, 1, 0); PG8_STAGE(PG8_SA(0, 1), a2 + hstepA, voffA);
;             PG8_WAIT_V(8); PG8_WAIT_L(0); PG8_BAR; PG8_MMA(0, 0, At, B0); PG8_MMA(0, 1, At, B1); PG8_BAR; PG8_SCHED;
	v_mfma_f32_16x16x32_bf16 v[60:63], v[80:83], v[186:189], v[60:63]
	v_mfma_f32_16x16x32_bf16 v[56:59], v[92:95], v[186:189], v[56:59]
	v_mfma_f32_16x16x32_bf16 v[44:47], v[80:83], v[194:197], v[44:47]
	v_mfma_f32_16x16x32_bf16 v[40:43], v[92:95], v[194:197], v[40:43]
	v_mfma_f32_16x16x32_bf16 v[28:31], v[80:83], v[202:205], v[28:31]
	v_mfma_f32_16x16x32_bf16 v[24:27], v[92:95], v[202:205], v[24:27]
	v_mfma_f32_16x16x32_bf16 v[12:15], v[80:83], v[210:213], v[12:15]
	v_mfma_f32_16x16x32_bf16 v[8:11], v[92:95], v[210:213], v[8:11]
	v_mfma_f32_16x16x32_bf16 v[60:63], v[88:91], v[190:193], v[60:63]
	v_mfma_f32_16x16x32_bf16 v[56:59], v[96:99], v[190:193], v[56:59]
	v_mfma_f32_16x16x32_bf16 v[44:47], v[88:91], v[198:201], v[44:47]
	v_mfma_f32_16x16x32_bf16 v[40:43], v[96:99], v[198:201], v[40:43]
	v_mfma_f32_16x16x32_bf16 v[28:31], v[88:91], v[206:209], v[28:31]
	v_mfma_f32_16x16x32_bf16 v[24:27], v[96:99], v[206:209], v[24:27]
	v_mfma_f32_16x16x32_bf16 v[12:15], v[88:91], v[214:217], v[12:15]
	v_mfma_f32_16x16x32_bf16 v[8:11], v[96:99], v[214:217], v[8:11]
	s_setprio 0
	s_setprio 1
	v_mfma_f32_16x16x32_bf16 v[52:55], v[162:165], v[186:189], v[52:55]
	v_mfma_f32_16x16x32_bf16 v[48:51], v[178:181], v[186:189], v[48:51]
	v_mfma_f32_16x16x32_bf16 v[36:39], v[162:165], v[194:197], v[36:39]
	v_mfma_f32_16x16x32_bf16 v[32:35], v[178:181], v[194:197], v[32:35]
	v_mfma_f32_16x16x32_bf16 v[20:23], v[162:165], v[202:205], v[20:23]
	v_mfma_f32_16x16x32_bf16 v[16:19], v[178:181], v[202:205], v[16:19]
	v_mfma_f32_16x16x32_bf16 v[4:7], v[162:165], v[210:213], v[4:7]
	v_mfma_f32_16x16x32_bf16 v[0:3], v[178:181], v[210:213], v[0:3]
	v_mfma_f32_16x16x32_bf16 v[52:55], v[166:169], v[190:193], v[52:55]
	v_mfma_f32_16x16x32_bf16 v[48:51], v[182:185], v[190:193], v[48:51]
	v_mfma_f32_16x16x32_bf16 v[36:39], v[166:169], v[198:201], v[36:39]
	v_mfma_f32_16x16x32_bf16 v[32:35], v[182:185], v[198:201], v[32:35]
	v_mfma_f32_16x16x32_bf16 v[20:23], v[166:169], v[206:209], v[20:23]
	v_mfma_f32_16x16x32_bf16 v[16:19], v[182:185], v[206:209], v[16:19]
	v_mfma_f32_16x16x32_bf16 v[4:7], v[166:169], v[214:217], v[4:7]
	v_mfma_f32_16x16x32_bf16 v[0:3], v[182:185], v[214:217], v[0:3]
	s_setprio 0
	s_barrier
	ds_read_b128 v[80:83], v175
	ds_read_b128 v[88:91], v175 offset:1024
	ds_read_b128 v[92:95], v175 offset:2048
	ds_read_b128 v[96:99], v175 offset:3072
	ds_read_b128 v[162:165], v176
	ds_read_b128 v[166:169], v176 offset:1024
	ds_read_b128 v[178:181], v176 offset:2048
	ds_read_b128 v[182:185], v176 offset:3072
	s_add_u32 s28, s28, 0x80000
	s_addc_u32 s29, s29, 0
	s_mov_b32 m0, s36
	v_lshl_add_u64 v[226:227], s[28:29], 0, v[144:145]
	ds_read_b128 v[186:189], v173 offset:32768
	ds_read_b128 v[190:193], v173 offset:33792
	ds_read_b128 v[194:197], v173 offset:34816
	ds_read_b128 v[198:201], v173 offset:35840
	ds_read_b128 v[202:205], v173 offset:36864
	ds_read_b128 v[206:209], v173 offset:37888
	ds_read_b128 v[210:213], v173 offset:38912
	ds_read_b128 v[214:217], v173 offset:39936
	global_load_lds_dwordx4 v[226:227], off
	s_mov_b32 m0, s37
	v_lshl_add_u64 v[226:227], s[28:29], 0, v[148:149]
	global_load_lds_dwordx4 v[226:227], off
	s_waitcnt vmcnt(8) lgkmcnt(0)
	s_setprio 1
	s_barrier
	v_mfma_f32_16x16x32_bf16 v[140:143], v[80:83], v[186:189], v[140:143]
	v_mfma_f32_16x16x32_bf16 v[136:139], v[92:95], v[186:189], v[136:139]
	v_mfma_f32_16x16x32_bf16 v[124:127], v[80:83], v[194:197], v[124:127]
	v_mfma_f32_16x16x32_bf16 v[120:123], v[92:95], v[194:197], v[120:123]
	v_mfma_f32_16x16x32_bf16 v[108:111], v[80:83], v[202:205], v[108:111]
	v_mfma_f32_16x16x32_bf16 v[104:107], v[92:95], v[202:205], v[104:107]
	v_mfma_f32_16x16x32_bf16 v[76:79], v[80:83], v[210:213], v[76:79]
	v_mfma_f32_16x16x32_bf16 v[72:75], v[92:95], v[210:213], v[72:75]
	v_mfma_f32_16x16x32_bf16 v[140:143], v[88:91], v[190:193], v[140:143]
	v_mfma_f32_16x16x32_bf16 v[136:139], v[96:99], v[190:193], v[136:139]
	v_mfma_f32_16x16x32_bf16 v[124:127], v[88:91], v[198:201], v[124:127]
	v_mfma_f32_16x16x32_bf16 v[120:123], v[96:99], v[198:201], v[120:123]
	v_mfma_f32_16x16x32_bf16 v[108:111], v[88:91], v[206:209], v[108:111]
	v_mfma_f32_16x16x32_bf16 v[104:107], v[96:99], v[206:209], v[104:107]
	v_mfma_f32_16x16x32_bf16 v[76:79], v[88:91], v[214:217], v[76:79]
	v_mfma_f32_16x16x32_bf16 v[72:75], v[96:99], v[214:217], v[72:75]
	s_setprio 0
	s_setprio 1
	v_mfma_f32_16x16x32_bf16 v[132:135], v[162:165], v[186:189], v[132:135]
	v_mfma_f32_16x16x32_bf16 v[128:131], v[178:181], v[186:189], v[128:131]
	v_mfma_f32_16x16x32_bf16 v[116:119], v[162:165], v[194:197], v[116:119]
	v_mfma_f32_16x16x32_bf16 v[112:115], v[178:181], v[194:197], v[112:115]
	v_mfma_f32_16x16x32_bf16 v[100:103], v[162:165], v[202:205], v[100:103]
	v_mfma_f32_16x16x32_bf16 v[84:87], v[178:181], v[202:205], v[84:87]
	v_mfma_f32_16x16x32_bf16 v[68:71], v[162:165], v[210:213], v[68:71]
	v_mfma_f32_16x16x32_bf16 v[64:67], v[178:181], v[210:213], v[64:67]
	v_mfma_f32_16x16x32_bf16 v[132:135], v[166:169], v[190:193], v[132:135]
	v_mfma_f32_16x16x32_bf16 v[128:131], v[182:185], v[190:193], v[128:131]
	v_mfma_f32_16x16x32_bf16 v[116:119], v[166:169], v[198:201], v[116:119]
	v_mfma_f32_16x16x32_bf16 v[112:115], v[182:185], v[198:201], v[112:115]
	v_mfma_f32_16x16x32_bf16 v[100:103], v[166:169], v[206:209], v[100:103]
	v_mfma_f32_16x16x32_bf16 v[84:87], v[182:185], v[206:209], v[84:87]
	v_mfma_f32_16x16x32_bf16 v[68:71], v[166:169], v[214:217], v[68:71]
	v_mfma_f32_16x16x32_bf16 v[64:67], v[182:185], v[214:217], v[64:67]
	s_setprio 0
	s_barrier
; #define PG8_STAGE(bufoff, gbase, voff) do { _Pragma("unroll") for (int _i = 0; _i < 2; ++_i) \
;         __builtin_amdgcn_global_load_lds((const unsigned*)((const char*)(gbase) + (voff)[_i]), (LAS unsigned*)(lds + (bufoff) + ldsw + _i * 8192), 16, 0, 0); } while (0)
; #define PG8_LDA(dst, b, h) do { _Pragma("unroll") for (int m = 0; m < 4; ++m) _Pragma("unroll") for (int k = 0; k < 2; ++k) dst[m][k] = *(const LAS bf16x8*)(lds + PG8_SA(b, h) + aoff + m * 2048 + k * 1024); } while (0)
; #define PG8_MMA(ai, bj, At, Bt) do { __builtin_amdgcn_s_setprio(1); _Pragma("unroll") for (int m = 0; m < 4; ++m) _Pragma("unroll") for (int n = 0; n < 2; ++n) _Pragma("unroll") for (int k = 0; k < 2; ++k) \
;         acc[ai][bj][m][n] = __builtin_amdgcn_mfma_f32_16x16x32_bf16(Bt[n][k], At[m][k], acc[ai][bj][m][n], 0, 0, 0); __builtin_amdgcn_s_setprio(0); } while (0)
; #define PG8_WAIT_V(n) asm volatile("s_waitcnt vmcnt(" #n ")" ::: "memory")
; #define PG8_WAIT_L(n) asm volatile("s_waitcnt lgkmcnt(" #n ")" ::: "memory")
; #define PG8_BAR __builtin_amdgcn_s_barrier()
; #define PG8_SCHED __builtin_amdgcn_sched_barrier(0)
; template <class Epi, class Sched, bool ALIGN_EPI = false, bool SP2 = false>
; __device__ __forceinline__ void gemm_phase(LAS unsigned char* lds, const Gemm g, const Sched& S, const Epi& E) {
;     ...
;             PG8_LDA(At, 1, 1); PG8_STAGE(PG8_SB(1, 0), b3, voffB); PG8_STAGE(PG8_SB(1, 1), b3 + hstepB, voffB); PG8_STAGE(PG8_SA(1, 0), a3, voffA);
;             PG8_WAIT_V(8); PG8_WAIT_L(0); PG8_BAR; PG8_MMA(1, 0, At, B0); PG8_MMA(1, 1, At, B1); PG8_BAR; PG8_SCHED;
;     ...
;         if constexpr (ALIGN_EPI) { if (wr == 0) PG8_BAR; }
	s_add_i32 s28, s47, s30
	v_lshl_add_u64 v[218:219], v[218:219], 0, s[8:9]
	s_mov_b32 m0, s28
	ds_read_b128 v[186:189], v173 offset:49152
	ds_read_b128 v[190:193], v173 offset:50176
	ds_read_b128 v[194:197], v173 offset:51200
	ds_read_b128 v[198:201], v173 offset:52224
	ds_read_b128 v[202:205], v173 offset:53248
	ds_read_b128 v[206:209], v173 offset:54272
	ds_read_b128 v[210:213], v173 offset:55296
	ds_read_b128 v[214:217], v173 offset:56320
	global_load_lds_dwordx4 v[218:219], off
	s_add_i32 m0, s28, 0x2000
	s_add_u32 s26, s26, 0x80080
	v_lshl_add_u64 v[218:219], v[220:221], 0, s[8:9]
	s_addc_u32 s27, s27, 0
	s_add_i32 s28, s48, s30
	global_load_lds_dwordx4 v[218:219], off
	s_mov_b32 m0, s28
	v_lshl_add_u64 v[218:219], s[26:27], 0, v[146:147]
	global_load_lds_dwordx4 v[218:219], off
	s_add_i32 m0, s28, 0x2000
	v_lshl_add_u64 v[218:219], s[26:27], 0, v[150:151]
	global_load_lds_dwordx4 v[218:219], off
	s_mov_b32 m0, s40
	v_lshl_add_u64 v[218:219], v[222:223], 0, s[8:9]
	global_load_lds_dwordx4 v[218:219], off
	s_mov_b32 m0, s41
	v_lshl_add_u64 v[218:219], v[224:225], 0, s[8:9]
	global_load_lds_dwordx4 v[218:219], off
	s_waitcnt vmcnt(8) lgkmcnt(0)
	s_setprio 1
	s_barrier
	v_mfma_f32_16x16x32_bf16 v[60:63], v[80:83], v[186:189], v[60:63]
	v_mfma_f32_16x16x32_bf16 v[56:59], v[92:95], v[186:189], v[56:59]
	v_mfma_f32_16x16x32_bf16 v[44:47], v[80:83], v[194:197], v[44:47]
	v_mfma_f32_16x16x32_bf16 v[40:43], v[92:95], v[194:197], v[40:43]
	v_mfma_f32_16x16x32_bf16 v[28:31], v[80:83], v[202:205], v[28:31]
	v_mfma_f32_16x16x32_bf16 v[24:27], v[92:95], v[202:205], v[24:27]
	v_mfma_f32_16x16x32_bf16 v[12:15], v[80:83], v[210:213], v[12:15]
	v_mfma_f32_16x16x32_bf16 v[8:11], v[92:95], v[210:213], v[8:11]
	v_mfma_f32_16x16x32_bf16 v[60:63], v[88:91], v[190:193], v[60:63]
	v_mfma_f32_16x16x32_bf16 v[56:59], v[96:99], v[190:193], v[56:59]
	v_mfma_f32_16x16x32_bf16 v[44:47], v[88:91], v[198:201], v[44:47]
	v_mfma_f32_16x16x32_bf16 v[40:43], v[96:99], v[198:201], v[40:43]
	v_mfma_f32_16x16x32_bf16 v[28:31], v[88:91], v[206:209], v[28:31]
	v_mfma_f32_16x16x32_bf16 v[24:27], v[96:99], v[206:209], v[24:27]
	v_mfma_f32_16x16x32_bf16 v[12:15], v[88:91], v[214:217], v[12:15]
	v_mfma_f32_16x16x32_bf16 v[8:11], v[96:99], v[214:217], v[8:11]
	s_setprio 0
	s_setprio 1
	v_mfma_f32_16x16x32_bf16 v[52:55], v[162:165], v[186:189], v[52:55]
	v_mfma_f32_16x16x32_bf16 v[48:51], v[178:181], v[186:189], v[48:51]
	v_mfma_f32_16x16x32_bf16 v[36:39], v[162:165], v[194:197], v[36:39]
	v_mfma_f32_16x16x32_bf16 v[32:35], v[178:181], v[194:197], v[32:35]
	v_mfma_f32_16x16x32_bf16 v[20:23], v[162:165], v[202:205], v[20:23]
	v_mfma_f32_16x16x32_bf16 v[16:19], v[178:181], v[202:205], v[16:19]
	v_mfma_f32_16x16x32_bf16 v[4:7], v[162:165], v[210:213], v[4:7]
	v_mfma_f32_16x16x32_bf16 v[0:3], v[178:181], v[210:213], v[0:3]
	v_mfma_f32_16x16x32_bf16 v[52:55], v[166:169], v[190:193], v[52:55]
	v_mfma_f32_16x16x32_bf16 v[48:51], v[182:185], v[190:193], v[48:51]
	v_mfma_f32_16x16x32_bf16 v[36:39], v[166:169], v[198:201], v[36:39]
	v_mfma_f32_16x16x32_bf16 v[32:35], v[182:185], v[198:201], v[32:35]
	v_mfma_f32_16x16x32_bf16 v[20:23], v[166:169], v[206:209], v[20:23]
	v_mfma_f32_16x16x32_bf16 v[16:19], v[182:185], v[206:209], v[16:19]
	v_mfma_f32_16x16x32_bf16 v[4:7], v[166:169], v[214:217], v[4:7]
	v_mfma_f32_16x16x32_bf16 v[0:3], v[182:185], v[214:217], v[0:3]
	s_add_i32 s53, s53, 2
	s_add_u32 s24, s24, 0x100
	s_addc_u32 s25, s25, 0
	s_add_u32 s51, s51, 0x100
	s_addc_u32 s52, s52, 0
	s_setprio 0
	s_barrier
	s_cmp_gt_u32 s53, 29
	s_cbranch_scc0 .LBB0_1055
	s_and_b64 vcc, exec, s[10:11]
	s_cbranch_vccz .LBB0_1058
	s_barrier

; #define PG8_STAGE(bufoff, gbase, voff) do { _Pragma("unroll") for (int _i = 0; _i < 2; ++_i) \
;         __builtin_amdgcn_global_load_lds((const unsigned*)((const char*)(gbase) + (voff)[_i]), (LAS unsigned*)(lds + (bufoff) + ldsw + _i * 8192), 16, 0, 0); } while (0)
; #define PG8_LDA(dst, b, h) do { _Pragma("unroll") for (int m = 0; m < 4; ++m) _Pragma("unroll") for (int k = 0; k < 2; ++k) dst[m][k] = *(const LAS bf16x8*)(lds + PG8_SA(b, h) + aoff + m * 2048 + k * 1024); } while (0)
; #define PG8_LDB(dst, b, h) do { _Pragma("unroll") for (int n = 0; n < 2; ++n) _Pragma("unroll") for (int k = 0; k < 2; ++k) dst[n][k] = *(const LAS bf16x8*)(lds + PG8_SB(b, h) + boff + n * 2048 + k * 1024); } while (0)
; #define PG8_MMA(ai, bj, At, Bt) do { __builtin_amdgcn_s_setprio(1); _Pragma("unroll") for (int m = 0; m < 4; ++m) _Pragma("unroll") for (int n = 0; n < 2; ++n) _Pragma("unroll") for (int k = 0; k < 2; ++k) \
;         acc[ai][bj][m][n] = __builtin_amdgcn_mfma_f32_16x16x32_bf16(Bt[n][k], At[m][k], acc[ai][bj][m][n], 0, 0, 0); __builtin_amdgcn_s_setprio(0); } while (0)
; #define PG8_BAR __builtin_amdgcn_s_barrier()
; template <class Epi, class Sched, bool ALIGN_EPI = false, bool SP2 = false>
; __device__ __forceinline__ void gemm_phase(LAS unsigned char* lds, const Gemm g, const Sched& S, const Epi& E) {
;     ...
;         const bool has_next = S.next(ui + 1, nxt);
;         const char* nA = has_next ? (const char*)g.A + (size_t)nxt.pm * tstepA : cA; const char* nB = has_next ? (const char*)g.Bt + (size_t)nxt.pn * tstepB : cB;
;         for (int t = 0; t < nt; t += 2) {
;             const bool last = (t == nt - 2);
;             const char* a1 = cA + (size_t)(t + 1) * kstep;
;             const char* a2 = last ? nA : cA + (size_t)(t + 2) * kstep; const char* b2 = last ? nB : cB + (size_t)(t + 2) * kstep;
;             const char* a3 = a2 + kstep; const char* b3 = b2 + kstep;
;             if (last && has_next) S.a_ready(nxt);
;             if constexpr (SP2) {
;             PG8_LDB(B0, 0, 0); PG8_LDB(B1, 0, 1); PG8_SCHED; PG8_LDA(At, 0, 0); PG8_STAGE(PG8_SA(1, 1), a1 + hstepA, voffA);
;             PG8_WAIT_V(8); PG8_WAIT_L(0); PG8_BAR; PG8_MMA(0, 0, At, B0); PG8_MMA(0, 1, At, B1); PG8_BAR; PG8_SCHED;
;             PG8_LDA(At, 0, 1); PG8_STAGE(PG8_SB(0, 0), b2, voffB); PG8_STAGE(PG8_SB(0, 1), b2 + hstepB, voffB); PG8_STAGE(PG8_SA(0, 0), a2, voffA);
.LBB0_1138:
	ds_read_b128 v[128:131], v176
	ds_read_b128 v[132:135], v176 offset:1024
	ds_read_b128 v[152:155], v176 offset:2048
	ds_read_b128 v[156:159], v176 offset:3072
	ds_read_b128 v[160:163], v177
	ds_read_b128 v[164:167], v177 offset:1024
	ds_read_b128 v[168:171], v177 offset:2048
	ds_read_b128 v[182:185], v177 offset:3072
	s_add_u32 s22, s20, 0xffea0080
	s_addc_u32 s23, s21, -1
	s_cmpk_eq_i32 s49, 0x54
	s_cselect_b32 s25, s3, s23
	s_cselect_b32 s24, s2, s22
	s_cselect_b32 s23, s19, s48
	s_cselect_b32 s22, s18, s47
	v_lshl_add_u64 v[172:173], s[20:21], 0, v[144:145]
	s_add_i32 m0, s28, 0xc000
	ds_read_b128 v[186:189], v178
	ds_read_b128 v[190:193], v178 offset:1024
	ds_read_b128 v[194:197], v178 offset:2048
	ds_read_b128 v[198:201], v178 offset:3072
	ds_read_b128 v[202:205], v178 offset:4096
	ds_read_b128 v[206:209], v178 offset:5120
	ds_read_b128 v[210:213], v178 offset:6144
	ds_read_b128 v[214:217], v178 offset:7168
	global_load_lds_dwordx4 v[172:173], off
	s_add_i32 m0, s28, 0xe000
	v_lshl_add_u64 v[172:173], s[20:21], 0, v[146:147]
	global_load_lds_dwordx4 v[172:173], off
	s_waitcnt vmcnt(8) lgkmcnt(0)
	s_setprio 1
	s_barrier
	v_mfma_f32_16x16x32_bf16 v[124:127], v[128:131], v[186:189], v[124:127]
	v_mfma_f32_16x16x32_bf16 v[120:123], v[152:155], v[186:189], v[120:123]
	v_mfma_f32_16x16x32_bf16 v[116:119], v[128:131], v[194:197], v[116:119]
	v_mfma_f32_16x16x32_bf16 v[112:115], v[152:155], v[194:197], v[112:115]
	v_mfma_f32_16x16x32_bf16 v[108:111], v[128:131], v[202:205], v[108:111]
	v_mfma_f32_16x16x32_bf16 v[104:107], v[152:155], v[202:205], v[104:107]
	v_mfma_f32_16x16x32_bf16 v[100:103], v[128:131], v[210:213], v[100:103]
	v_mfma_f32_16x16x32_bf16 v[96:99], v[152:155], v[210:213], v[96:99]
	v_mfma_f32_16x16x32_bf16 v[124:127], v[132:135], v[190:193], v[124:127]
	v_mfma_f32_16x16x32_bf16 v[120:123], v[156:159], v[190:193], v[120:123]
	v_mfma_f32_16x16x32_bf16 v[116:119], v[132:135], v[198:201], v[116:119]
	v_mfma_f32_16x16x32_bf16 v[112:115], v[156:159], v[198:201], v[112:115]
	v_mfma_f32_16x16x32_bf16 v[108:111], v[132:135], v[206:209], v[108:111]
	v_mfma_f32_16x16x32_bf16 v[104:107], v[156:159], v[206:209], v[104:107]
	v_mfma_f32_16x16x32_bf16 v[100:103], v[132:135], v[214:217], v[100:103]
	v_mfma_f32_16x16x32_bf16 v[96:99], v[156:159], v[214:217], v[96:99]
	s_setprio 0
	s_setprio 1
	v_mfma_f32_16x16x32_bf16 v[68:71], v[160:163], v[186:189], v[68:71]
	v_mfma_f32_16x16x32_bf16 v[60:63], v[168:171], v[186:189], v[60:63]
	v_mfma_f32_16x16x32_bf16 v[52:55], v[160:163], v[194:197], v[52:55]
	v_mfma_f32_16x16x32_bf16 v[48:51], v[168:171], v[194:197], v[48:51]
	v_mfma_f32_16x16x32_bf16 v[44:47], v[160:163], v[202:205], v[44:47]
	v_mfma_f32_16x16x32_bf16 v[40:43], v[168:171], v[202:205], v[40:43]
	v_mfma_f32_16x16x32_bf16 v[36:39], v[160:163], v[210:213], v[36:39]
	v_mfma_f32_16x16x32_bf16 v[32:35], v[168:171], v[210:213], v[32:35]
	v_mfma_f32_16x16x32_bf16 v[68:71], v[164:167], v[190:193], v[68:71]
	v_mfma_f32_16x16x32_bf16 v[60:63], v[182:185], v[190:193], v[60:63]
	v_mfma_f32_16x16x32_bf16 v[52:55], v[164:167], v[198:201], v[52:55]
	v_mfma_f32_16x16x32_bf16 v[48:51], v[182:185], v[198:201], v[48:51]
	v_mfma_f32_16x16x32_bf16 v[44:47], v[164:167], v[206:209], v[44:47]
	v_mfma_f32_16x16x32_bf16 v[40:43], v[182:185], v[206:209], v[40:43]
	v_mfma_f32_16x16x32_bf16 v[36:39], v[164:167], v[214:217], v[36:39]
	v_mfma_f32_16x16x32_bf16 v[32:35], v[182:185], v[214:217], v[32:35]
	s_setprio 0
	s_barrier
	s_add_i32 s50, s40, s27
	v_lshl_add_u64 v[172:173], s[22:23], 0, v[138:139]
	s_mov_b32 m0, s50
	ds_read_b128 v[186:189], v178 offset:16384
	ds_read_b128 v[190:193], v178 offset:17408
	ds_read_b128 v[194:197], v178 offset:18432
	ds_read_b128 v[198:201], v178 offset:19456
	ds_read_b128 v[202:205], v178 offset:20480
	ds_read_b128 v[206:209], v178 offset:21504
	ds_read_b128 v[210:213], v178 offset:22528
	ds_read_b128 v[214:217], v178 offset:23552
	global_load_lds_dwordx4 v[172:173], off
	s_add_i32 m0, s50, 0x2000
	s_add_u32 s50, s22, 0x160000
	v_lshl_add_u64 v[218:219], s[22:23], 0, v[142:143]
	s_addc_u32 s51, s23, 0
	s_add_i32 s52, s41, s27
	global_load_lds_dwordx4 v[218:219], off
	v_lshl_add_u64 v[220:221], s[50:51], 0, v[138:139]
	s_mov_b32 m0, s52
	v_lshl_add_u64 v[222:223], s[24:25], 0, v[140:141]
	global_load_lds_dwordx4 v[220:221], off
	s_add_i32 m0, s52, 0x2000
	v_lshl_add_u64 v[220:221], s[50:51], 0, v[142:143]
	global_load_lds_dwordx4 v[220:221], off
	s_mov_b32 m0, s28
	v_lshl_add_u64 v[220:221], s[24:25], 0, v[136:137]
	global_load_lds_dwordx4 v[220:221], off
	s_mov_b32 m0, s29
	s_nop 0
	global_load_lds_dwordx4 v[222:223], off
	s_waitcnt vmcnt(8) lgkmcnt(0)
	s_setprio 1
	s_barrier
; #define PG8_STAGE(bufoff, gbase, voff) do { _Pragma("unroll") for (int _i = 0; _i < 2; ++_i) \
;         __builtin_amdgcn_global_load_lds((const unsigned*)((const char*)(gbase) + (voff)[_i]), (LAS unsigned*)(lds + (bufoff) + ldsw + _i * 8192), 16, 0, 0); } while (0)
; #define PG8_LDA(dst, b, h) do { _Pragma("unroll") for (int m = 0; m < 4; ++m) _Pragma("unroll") for (int k = 0; k < 2; ++k) dst[m][k] = *(const LAS bf16x8*)(lds + PG8_SA(b, h) + aoff + m * 2048 + k * 1024); } while (0)
; #define PG8_LDB(dst, b, h) do { _Pragma("unroll") for (int n = 0; n < 2; ++n) _Pragma("unroll") for (int k = 0; k < 2; ++k) dst[n][k] = *(const LAS bf16x8*)(lds + PG8_SB(b, h) + boff + n * 2048 + k * 1024); } while (0)
; #define PG8_MMA(ai, bj, At, Bt) do { __builtin_amdgcn_s_setprio(1); _Pragma("unroll") for (int m = 0; m < 4; ++m) _Pragma("unroll") for (int n = 0; n < 2; ++n) _Pragma("unroll") for (int k = 0; k < 2; ++k) \
;         acc[ai][bj][m][n] = __builtin_amdgcn_mfma_f32_16x16x32_bf16(Bt[n][k], At[m][k], acc[ai][bj][m][n], 0, 0, 0); __builtin_amdgcn_s_setprio(0); } while (0)
; #define PG8_WAIT_V(n) asm volatile("s_waitcnt vmcnt(" #n ")" ::: "memory")
; #define PG8_WAIT_L(n) asm volatile("s_waitcnt lgkmcnt(" #n ")" ::: "memory")
; #define PG8_BAR __builtin_amdgcn_s_barrier()
; #define PG8_SCHED __builtin_amdgcn_sched_barrier(0)
; template <class Epi, class Sched, bool ALIGN_EPI = false, bool SP2 = false>
; __device__ __forceinline__ void gemm_phase(LAS unsigned char* lds, const Gemm g, const Sched& S, const Epi& E) {
;     ...
;             PG8_WAIT_V(8); PG8_WAIT_L(0); PG8_BAR; PG8_MMA(1, 0, At, B0); PG8_MMA(1, 1, At, B1); PG8_BAR; PG8_SCHED;
;             PG8_LDB(B0, 1, 0); PG8_LDB(B1, 1, 1); PG8_SCHED; PG8_LDA(At, 1, 0); PG8_STAGE(PG8_SA(0, 1), a2 + hstepA, voffA);
;             PG8_WAIT_V(8); PG8_WAIT_L(0); PG8_BAR; PG8_MMA(0, 0, At, B0); PG8_MMA(0, 1, At, B1); PG8_BAR; PG8_SCHED;
	v_mfma_f32_16x16x32_bf16 v[92:95], v[128:131], v[186:189], v[92:95]
	v_mfma_f32_16x16x32_bf16 v[88:91], v[152:155], v[186:189], v[88:91]
	v_mfma_f32_16x16x32_bf16 v[84:87], v[128:131], v[194:197], v[84:87]
	v_mfma_f32_16x16x32_bf16 v[80:83], v[152:155], v[194:197], v[80:83]
	v_mfma_f32_16x16x32_bf16 v[76:79], v[128:131], v[202:205], v[76:79]
	v_mfma_f32_16x16x32_bf16 v[72:75], v[152:155], v[202:205], v[72:75]
	v_mfma_f32_16x16x32_bf16 v[64:67], v[128:131], v[210:213], v[64:67]
	v_mfma_f32_16x16x32_bf16 v[56:59], v[152:155], v[210:213], v[56:59]
	v_mfma_f32_16x16x32_bf16 v[92:95], v[132:135], v[190:193], v[92:95]
	v_mfma_f32_16x16x32_bf16 v[88:91], v[156:159], v[190:193], v[88:91]
	v_mfma_f32_16x16x32_bf16 v[84:87], v[132:135], v[198:201], v[84:87]
	v_mfma_f32_16x16x32_bf16 v[80:83], v[156:159], v[198:201], v[80:83]
	v_mfma_f32_16x16x32_bf16 v[76:79], v[132:135], v[206:209], v[76:79]
	v_mfma_f32_16x16x32_bf16 v[72:75], v[156:159], v[206:209], v[72:75]
	v_mfma_f32_16x16x32_bf16 v[64:67], v[132:135], v[214:217], v[64:67]
	v_mfma_f32_16x16x32_bf16 v[56:59], v[156:159], v[214:217], v[56:59]
	s_setprio 0
	s_setprio 1
	v_mfma_f32_16x16x32_bf16 v[28:31], v[160:163], v[186:189], v[28:31]
	v_mfma_f32_16x16x32_bf16 v[24:27], v[168:171], v[186:189], v[24:27]
	v_mfma_f32_16x16x32_bf16 v[20:23], v[160:163], v[194:197], v[20:23]
	v_mfma_f32_16x16x32_bf16 v[16:19], v[168:171], v[194:197], v[16:19]
	v_mfma_f32_16x16x32_bf16 v[12:15], v[160:163], v[202:205], v[12:15]
	v_mfma_f32_16x16x32_bf16 v[8:11], v[168:171], v[202:205], v[8:11]
	v_mfma_f32_16x16x32_bf16 v[4:7], v[160:163], v[210:213], v[4:7]
	v_mfma_f32_16x16x32_bf16 v[0:3], v[168:171], v[210:213], v[0:3]
	v_mfma_f32_16x16x32_bf16 v[28:31], v[164:167], v[190:193], v[28:31]
	v_mfma_f32_16x16x32_bf16 v[24:27], v[182:185], v[190:193], v[24:27]
	v_mfma_f32_16x16x32_bf16 v[20:23], v[164:167], v[198:201], v[20:23]
	v_mfma_f32_16x16x32_bf16 v[16:19], v[182:185], v[198:201], v[16:19]
	v_mfma_f32_16x16x32_bf16 v[12:15], v[164:167], v[206:209], v[12:15]
	v_mfma_f32_16x16x32_bf16 v[8:11], v[182:185], v[206:209], v[8:11]
	v_mfma_f32_16x16x32_bf16 v[4:7], v[164:167], v[214:217], v[4:7]
	v_mfma_f32_16x16x32_bf16 v[0:3], v[182:185], v[214:217], v[0:3]
	s_setprio 0
	s_barrier
	ds_read_b128 v[128:131], v179
	ds_read_b128 v[132:135], v179 offset:1024
	ds_read_b128 v[152:155], v179 offset:2048
	ds_read_b128 v[156:159], v179 offset:3072
	ds_read_b128 v[160:163], v180
	ds_read_b128 v[164:167], v180 offset:1024
	ds_read_b128 v[168:171], v180 offset:2048
	ds_read_b128 v[182:185], v180 offset:3072
	s_add_u32 s24, s24, 0x160000
	s_addc_u32 s25, s25, 0
	s_mov_b32 m0, s30
	v_lshl_add_u64 v[224:225], s[24:25], 0, v[136:137]
	ds_read_b128 v[186:189], v178 offset:32768
	ds_read_b128 v[190:193], v178 offset:33792
	ds_read_b128 v[194:197], v178 offset:34816
	ds_read_b128 v[198:201], v178 offset:35840
	ds_read_b128 v[202:205], v178 offset:36864
	ds_read_b128 v[206:209], v178 offset:37888
	ds_read_b128 v[210:213], v178 offset:38912
	ds_read_b128 v[214:217], v178 offset:39936
	global_load_lds_dwordx4 v[224:225], off
	s_mov_b32 m0, s31
	v_lshl_add_u64 v[224:225], s[24:25], 0, v[140:141]
	global_load_lds_dwordx4 v[224:225], off
	s_waitcnt vmcnt(8) lgkmcnt(0)
	s_setprio 1
	s_barrier
	v_mfma_f32_16x16x32_bf16 v[124:127], v[128:131], v[186:189], v[124:127]
	v_mfma_f32_16x16x32_bf16 v[120:123], v[152:155], v[186:189], v[120:123]
	v_mfma_f32_16x16x32_bf16 v[116:119], v[128:131], v[194:197], v[116:119]
	v_mfma_f32_16x16x32_bf16 v[112:115], v[152:155], v[194:197], v[112:115]
	v_mfma_f32_16x16x32_bf16 v[108:111], v[128:131], v[202:205], v[108:111]
	v_mfma_f32_16x16x32_bf16 v[104:107], v[152:155], v[202:205], v[104:107]
	v_mfma_f32_16x16x32_bf16 v[100:103], v[128:131], v[210:213], v[100:103]
	v_mfma_f32_16x16x32_bf16 v[96:99], v[152:155], v[210:213], v[96:99]
	v_mfma_f32_16x16x32_bf16 v[124:127], v[132:135], v[190:193], v[124:127]
	v_mfma_f32_16x16x32_bf16 v[120:123], v[156:159], v[190:193], v[120:123]
	v_mfma_f32_16x16x32_bf16 v[116:119], v[132:135], v[198:201], v[116:119]
	v_mfma_f32_16x16x32_bf16 v[112:115], v[156:159], v[198:201], v[112:115]
	v_mfma_f32_16x16x32_bf16 v[108:111], v[132:135], v[206:209], v[108:111]
	v_mfma_f32_16x16x32_bf16 v[104:107], v[156:159], v[206:209], v[104:107]
	v_mfma_f32_16x16x32_bf16 v[100:103], v[132:135], v[214:217], v[100:103]
	v_mfma_f32_16x16x32_bf16 v[96:99], v[156:159], v[214:217], v[96:99]
	s_setprio 0
	s_setprio 1
	v_mfma_f32_16x16x32_bf16 v[68:71], v[160:163], v[186:189], v[68:71]
	v_mfma_f32_16x16x32_bf16 v[60:63], v[168:171], v[186:189], v[60:63]
	v_mfma_f32_16x16x32_bf16 v[52:55], v[160:163], v[194:197], v[52:55]
	v_mfma_f32_16x16x32_bf16 v[48:51], v[168:171], v[194:197], v[48:51]
	v_mfma_f32_16x16x32_bf16 v[44:47], v[160:163], v[202:205], v[44:47]
	v_mfma_f32_16x16x32_bf16 v[40:43], v[168:171], v[202:205], v[40:43]
	v_mfma_f32_16x16x32_bf16 v[36:39], v[160:163], v[210:213], v[36:39]
	v_mfma_f32_16x16x32_bf16 v[32:35], v[168:171], v[210:213], v[32:35]
	v_mfma_f32_16x16x32_bf16 v[68:71], v[164:167], v[190:193], v[68:71]
	v_mfma_f32_16x16x32_bf16 v[60:63], v[182:185], v[190:193], v[60:63]
	v_mfma_f32_16x16x32_bf16 v[52:55], v[164:167], v[198:201], v[52:55]
	v_mfma_f32_16x16x32_bf16 v[48:51], v[182:185], v[198:201], v[48:51]
	v_mfma_f32_16x16x32_bf16 v[44:47], v[164:167], v[206:209], v[44:47]
	v_mfma_f32_16x16x32_bf16 v[40:43], v[182:185], v[206:209], v[40:43]
	v_mfma_f32_16x16x32_bf16 v[36:39], v[164:167], v[214:217], v[36:39]
	v_mfma_f32_16x16x32_bf16 v[32:35], v[182:185], v[214:217], v[32:35]
	s_setprio 0
	s_barrier
; #define PG8_STAGE(bufoff, gbase, voff) do { _Pragma("unroll") for (int _i = 0; _i < 2; ++_i) \
;         __builtin_amdgcn_global_load_lds((const unsigned*)((const char*)(gbase) + (voff)[_i]), (LAS unsigned*)(lds + (bufoff) + ldsw + _i * 8192), 16, 0, 0); } while (0)
; #define PG8_LDA(dst, b, h) do { _Pragma("unroll") for (int m = 0; m < 4; ++m) _Pragma("unroll") for (int k = 0; k < 2; ++k) dst[m][k] = *(const LAS bf16x8*)(lds + PG8_SA(b, h) + aoff + m * 2048 + k * 1024); } while (0)
; #define PG8_MMA(ai, bj, At, Bt) do { __builtin_amdgcn_s_setprio(1); _Pragma("unroll") for (int m = 0; m < 4; ++m) _Pragma("unroll") for (int n = 0; n < 2; ++n) _Pragma("unroll") for (int k = 0; k < 2; ++k) \
;         acc[ai][bj][m][n] = __builtin_amdgcn_mfma_f32_16x16x32_bf16(Bt[n][k], At[m][k], acc[ai][bj][m][n], 0, 0, 0); __builtin_amdgcn_s_setprio(0); } while (0)
; #define PG8_WAIT_V(n) asm volatile("s_waitcnt vmcnt(" #n ")" ::: "memory")
; #define PG8_WAIT_L(n) asm volatile("s_waitcnt lgkmcnt(" #n ")" ::: "memory")
; #define PG8_BAR __builtin_amdgcn_s_barrier()
; #define PG8_SCHED __builtin_amdgcn_sched_barrier(0)
; template <class Epi, class Sched, bool ALIGN_EPI = false, bool SP2 = false>
; __device__ __forceinline__ void gemm_phase(LAS unsigned char* lds, const Gemm g, const Sched& S, const Epi& E) {
;     ...
;             PG8_LDA(At, 1, 1); PG8_STAGE(PG8_SB(1, 0), b3, voffB); PG8_STAGE(PG8_SB(1, 1), b3 + hstepB, voffB); PG8_STAGE(PG8_SA(1, 0), a3, voffA);
;             PG8_WAIT_V(8); PG8_WAIT_L(0); PG8_BAR; PG8_MMA(1, 0, At, B0); PG8_MMA(1, 1, At, B1); PG8_BAR; PG8_SCHED;
;     ...
;         if constexpr (ALIGN_EPI) { if (wr == 0) PG8_BAR; }
	s_add_i32 s24, s42, s27
	v_lshl_add_u64 v[172:173], v[172:173], 0, s[8:9]
	s_mov_b32 m0, s24
	ds_read_b128 v[186:189], v178 offset:49152
	ds_read_b128 v[190:193], v178 offset:50176
	ds_read_b128 v[194:197], v178 offset:51200
	ds_read_b128 v[198:201], v178 offset:52224
	ds_read_b128 v[202:205], v178 offset:53248
	ds_read_b128 v[206:209], v178 offset:54272
	ds_read_b128 v[210:213], v178 offset:55296
	ds_read_b128 v[214:217], v178 offset:56320
	global_load_lds_dwordx4 v[172:173], off
	s_add_i32 m0, s24, 0x2000
	s_add_u32 s22, s22, 0x160080
	v_lshl_add_u64 v[172:173], v[218:219], 0, s[8:9]
	s_addc_u32 s23, s23, 0
	s_add_i32 s24, s43, s27
	global_load_lds_dwordx4 v[172:173], off
	s_mov_b32 m0, s24
	v_lshl_add_u64 v[172:173], s[22:23], 0, v[138:139]
	global_load_lds_dwordx4 v[172:173], off
	s_add_i32 m0, s24, 0x2000
	v_lshl_add_u64 v[172:173], s[22:23], 0, v[142:143]
	global_load_lds_dwordx4 v[172:173], off
	s_mov_b32 m0, s36
	v_lshl_add_u64 v[172:173], v[220:221], 0, s[8:9]
	global_load_lds_dwordx4 v[172:173], off
	s_mov_b32 m0, s37
	v_lshl_add_u64 v[172:173], v[222:223], 0, s[8:9]
	global_load_lds_dwordx4 v[172:173], off
	s_waitcnt vmcnt(8) lgkmcnt(0)
	s_setprio 1
	s_barrier
	v_mfma_f32_16x16x32_bf16 v[92:95], v[128:131], v[186:189], v[92:95]
	v_mfma_f32_16x16x32_bf16 v[88:91], v[152:155], v[186:189], v[88:91]
	v_mfma_f32_16x16x32_bf16 v[84:87], v[128:131], v[194:197], v[84:87]
	v_mfma_f32_16x16x32_bf16 v[80:83], v[152:155], v[194:197], v[80:83]
	v_mfma_f32_16x16x32_bf16 v[76:79], v[128:131], v[202:205], v[76:79]
	v_mfma_f32_16x16x32_bf16 v[72:75], v[152:155], v[202:205], v[72:75]
	v_mfma_f32_16x16x32_bf16 v[64:67], v[128:131], v[210:213], v[64:67]
	v_mfma_f32_16x16x32_bf16 v[56:59], v[152:155], v[210:213], v[56:59]
	v_mfma_f32_16x16x32_bf16 v[92:95], v[132:135], v[190:193], v[92:95]
	v_mfma_f32_16x16x32_bf16 v[88:91], v[156:159], v[190:193], v[88:91]
	v_mfma_f32_16x16x32_bf16 v[84:87], v[132:135], v[198:201], v[84:87]
	v_mfma_f32_16x16x32_bf16 v[80:83], v[156:159], v[198:201], v[80:83]
	v_mfma_f32_16x16x32_bf16 v[76:79], v[132:135], v[206:209], v[76:79]
	v_mfma_f32_16x16x32_bf16 v[72:75], v[156:159], v[206:209], v[72:75]
	v_mfma_f32_16x16x32_bf16 v[64:67], v[132:135], v[214:217], v[64:67]
	v_mfma_f32_16x16x32_bf16 v[56:59], v[156:159], v[214:217], v[56:59]
	s_setprio 0
	s_setprio 1
	v_mfma_f32_16x16x32_bf16 v[28:31], v[160:163], v[186:189], v[28:31]
	v_mfma_f32_16x16x32_bf16 v[24:27], v[168:171], v[186:189], v[24:27]
	v_mfma_f32_16x16x32_bf16 v[20:23], v[160:163], v[194:197], v[20:23]
	v_mfma_f32_16x16x32_bf16 v[16:19], v[168:171], v[194:197], v[16:19]
	v_mfma_f32_16x16x32_bf16 v[12:15], v[160:163], v[202:205], v[12:15]
	v_mfma_f32_16x16x32_bf16 v[8:11], v[168:171], v[202:205], v[8:11]
	v_mfma_f32_16x16x32_bf16 v[4:7], v[160:163], v[210:213], v[4:7]
	v_mfma_f32_16x16x32_bf16 v[0:3], v[168:171], v[210:213], v[0:3]
	v_mfma_f32_16x16x32_bf16 v[28:31], v[164:167], v[190:193], v[28:31]
	v_mfma_f32_16x16x32_bf16 v[24:27], v[182:185], v[190:193], v[24:27]
	v_mfma_f32_16x16x32_bf16 v[20:23], v[164:167], v[198:201], v[20:23]
	v_mfma_f32_16x16x32_bf16 v[16:19], v[182:185], v[198:201], v[16:19]
	v_mfma_f32_16x16x32_bf16 v[12:15], v[164:167], v[206:209], v[12:15]
	v_mfma_f32_16x16x32_bf16 v[8:11], v[182:185], v[206:209], v[8:11]
	v_mfma_f32_16x16x32_bf16 v[4:7], v[164:167], v[214:217], v[4:7]
	v_mfma_f32_16x16x32_bf16 v[0:3], v[182:185], v[214:217], v[0:3]
	s_setprio 0
	s_barrier
	s_add_i32 s49, s49, 2
	s_add_u32 s20, s20, 0x100
	s_addc_u32 s21, s21, 0
	s_add_u32 s47, s47, 0x100
	s_addc_u32 s48, s48, 0
	s_cmpk_gt_u32 s49, 0x55
	s_cbranch_scc0 .LBB0_1138
	s_and_b64 vcc, exec, s[10:11]
	s_cbranch_vccz .LBB0_1141
	s_barrier
